# last layer, last gate/up round: the two workgroups of a panel pair each compute one 128-row half of the tile (separate guarded K-loop copy)
# speedup vs baseline: 1.0023x; 1.0023x over previous
;     ...
;         if (!has_next) break;
; #pragma unroll
;         for (int a = 0; a < 2; ++a)
; #pragma unroll
;             for (int b = 0; b < 2; ++b)
; #pragma unroll
;                 for (int m = 0; m < 4; ++m)
; #pragma unroll
;                     for (int n = 0; n < 2; ++n) acc[a][b][m][n] = (f32x4){0.f, 0.f, 0.f, 0.f};
;         cur = nxt; cA = nA; cB = nB; ++ui;
.LBB0_603:
	s_lshr_b32 s101, s101, 2
	s_mov_b64 s[6:7], 0

;     __host__ __device__ bool next(int i, Unit& u) const {
;         const long L = (long)i * G + c; if (L >= nwg) return false;
;         int wgid = (int)L; { const int q = nwg / NXCD, r = nwg % NXCD, xcd = wgid % NXCD, off = wgid / NXCD; wgid = (xcd < r ? xcd * (q + 1) : r * (q + 1) + (xcd - r) * q) + off; }
;         const int nig = WGM * nN, gid = wgid / nig, fm = gid * WGM, gsz = (nM - fm) < WGM ? (nM - fm) : WGM;
;         u.pm = fm + ((wgid % nig) % gsz); u.pn = (wgid % nig) / gsz; return true;
;     }
;     ...
;         const bool has_next = S.next(ui + 1, nxt);
;         const char* nA = has_next ? (const char*)gA + (size_t)nxt.pm * tstepA + (size_t)nxt.pn * acolB : cA; const char* nB = has_next ? (const char*)gB + (size_t)nxt.pn * tstepB : cB;
.LBB0_605:
	s_add_i32 s19, s19, 1
	s_mul_i32 s6, s19, s37
	s_mul_hi_u32 s7, s19, s77
	s_add_i32 s7, s7, s6
	s_mul_i32 s6, s19, s77
	v_readlane_b32 s24, v254, 37
	v_readlane_b32 s25, v254, 38
	s_add_u32 s6, s6, s24
	s_addc_u32 s7, s7, s25
	s_and_b32 s101, s101, 3
	v_readlane_b32 s24, v254, 52
	s_cmp_lg_u32 s24, 3
	s_cbranch_scc1 .Lms_done
	s_cmp_lg_u32 s19, 5
	s_cbranch_scc1 .Lms_done
	s_or_b32 s101, s101, 4
	s_cmp_lt_u32 s6, 0x580
	s_cbranch_scc1 .Lms_done
	s_sub_u32 s6, s6, 0x80
	s_xor_b32 s101, s101, 12
.Lms_done:
	v_mov_b64_e32 v[2:3], 0x580
	v_cmp_lt_i64_e64 s[40:41], s[6:7], v[2:3]
	v_mov_b64_e32 v[2:3], 0x57f
	v_cmp_gt_i64_e32 vcc, s[6:7], v[2:3]
	s_cbranch_vccnz .LBB0_607
	s_ashr_i32 s7, s6, 31
	s_lshr_b32 s7, s7, 29
	s_add_i32 s7, s6, s7
	s_ashr_i32 s20, s7, 3
	s_and_b32 s7, s7, -8
	s_sub_i32 s6, s6, s7
	s_cmp_lt_i32 s6, 0
	s_movk_i32 s7, 0xb1
	s_cselect_b32 s7, s7, 0xb0
	s_mul_i32 s6, s6, s7
	s_add_i32 s6, s6, s20
	s_mul_hi_i32 s7, s6, 0x2e8ba2e9
	s_lshr_b32 s20, s7, 31
	s_ashr_i32 s7, s7, 5
	s_add_i32 s7, s7, s20
	s_lshl_b32 s21, s7, 3
	s_sub_i32 s20, 64, s21
	s_min_i32 s24, s20, 8
	s_abs_i32 s20, s24
	v_cvt_f32_u32_e32 v2, s20
	s_sub_i32 s27, 0, s20
	s_mulk_i32 s7, 0xb0
	s_sub_i32 s6, s6, s7
	v_rcp_iflag_f32_e32 v2, v2
	s_abs_i32 s7, s6
	s_xor_b32 s25, s6, s24
	s_ashr_i32 s25, s25, 31
	v_mul_f32_e32 v2, 0x4f7ffffe, v2
	v_cvt_u32_f32_e32 v2, v2
	s_nop 0
	v_readfirstlane_b32 s31, v2
	s_mul_i32 s27, s27, s31
	s_mul_hi_u32 s27, s31, s27
	s_add_i32 s31, s31, s27
	s_mul_hi_u32 s27, s7, s31
	s_mul_i32 s31, s27, s20
	s_sub_i32 s7, s7, s31
	s_add_i32 s33, s27, 1
	s_sub_i32 s31, s7, s20
	s_cmp_ge_u32 s7, s20
	s_cselect_b32 s27, s33, s27
	s_cselect_b32 s7, s31, s7
	s_add_i32 s31, s27, 1
	s_cmp_ge_u32 s7, s20
	s_cselect_b32 s7, s31, s27
	s_xor_b32 s7, s7, s25
	s_sub_i32 s20, s7, s25
	s_mul_i32 s7, s20, s24
	s_sub_i32 s6, s6, s7
	s_add_i32 s21, s21, s6

; #define PG8_STAGE(bufoff, gbase, voff) do { _Pragma("unroll") for (int _i = 0; _i < 2; ++_i) \
;         __builtin_amdgcn_global_load_lds((const unsigned*)((const char*)(gbase) + (voff)[_i]), (PG8_LAS unsigned*)(lds + (bufoff) + ldsw + _i * 8192), 16, 0, 0); } while (0)
; #define PG8_LDA(dst, b, h) do { _Pragma("unroll") for (int m = 0; m < 4; ++m) _Pragma("unroll") for (int k = 0; k < 2; ++k) dst[m][k] = *(const PG8_LAS bf16x8*)(lds + PG8_SA(b, h) + aoff + m * 2048 + k * 1024); } while (0)
; #define PG8_LDB(dst, b, h) do { _Pragma("unroll") for (int n = 0; n < 2; ++n) _Pragma("unroll") for (int k = 0; k < 2; ++k) dst[n][k] = *(const PG8_LAS bf16x8*)(lds + PG8_SB(b, h) + boff + n * 2048 + k * 1024); } while (0)
; #define PG8_MMA(ai, bj, At, Bt) do { __builtin_amdgcn_s_setprio(1); _Pragma("unroll") for (int m = 0; m < 4; ++m) _Pragma("unroll") for (int n = 0; n < 2; ++n) _Pragma("unroll") for (int k = 0; k < 2; ++k) \
;         acc[ai][bj][m][n] = __builtin_amdgcn_mfma_f32_16x16x32_bf16(Bt[n][k], At[m][k], acc[ai][bj][m][n], 0, 0, 0); __builtin_amdgcn_s_setprio(0); } while (0)
; #define PG8_WAIT_V(n) asm volatile("s_waitcnt vmcnt(" #n ")" ::: "memory")
; #define PG8_WAIT_L(n) asm volatile("s_waitcnt lgkmcnt(" #n ")" ::: "memory")
; #define PG8_BAR __builtin_amdgcn_s_barrier()
; #define PG8_SCHED __builtin_amdgcn_sched_barrier(0)
;     ...
;             PG8_LDB(B0, 0, 0); PG8_LDB(B1, 0, 1); PG8_SCHED; PG8_LDA(At, 0, 0); PG8_STAGE(PG8_SA(1, 1), a1 + hstepA, voffA);
;             PG8_WAIT_V(8); PG8_WAIT_L(0); PG8_BAR; PG8_MMA(0, 0, At, B0); PG8_MMA(0, 1, At, B1); PG8_BAR; PG8_SCHED;
;             PG8_LDA(At, 0, 1); PG8_STAGE(PG8_SB(0, 0), b2, voffB); PG8_STAGE(PG8_SB(0, 1), b2 + hstepB, voffB); PG8_STAGE(PG8_SA(0, 0), a2, voffA);
;             PG8_WAIT_V(8); PG8_WAIT_L(0); PG8_BAR; PG8_MMA(1, 0, At, B0); PG8_MMA(1, 1, At, B1); PG8_BAR; PG8_SCHED;
.LBB0_611:
	s_andn2_b64 vcc, exec, s[86:87]
	s_cbranch_vccnz .LBB0_614
	s_and_b32 s24, s101, 3
	s_cbranch_scc1 .Lhalf_entry
	s_add_u32 s24, s8, 0x100
	s_addc_u32 s25, s9, 0
	s_add_u32 s6, s10, 0x80
	s_addc_u32 s7, s11, 0
	s_mov_b32 s8, 0
	s_add_i32 s10, s8, 2
	s_add_u32 s11, s6, 0x80
	s_addc_u32 s9, s7, 0
	s_add_i32 s27, 0, 0x10000
	s_cmp_eq_u32 s18, s8
	s_cselect_b32 s9, s41, s9
	s_cselect_b32 s8, s40, s11
	v_add_u32_e32 v140, s27, v151
	s_cselect_b32 s35, s91, s25
	s_cselect_b32 s34, s90, s24
	s_add_i32 s11, 0, 0x14000
	ds_read_b128 v[156:159], v140
	ds_read_b128 v[160:163], v140 offset:1024
	ds_read_b128 v[172:175], v140 offset:2048
	ds_read_b128 v[176:179], v140 offset:3072
	v_add_u32_e32 v140, s11, v151
	ds_read_b128 v[180:183], v140
	ds_read_b128 v[184:187], v140 offset:1024
	ds_read_b128 v[188:191], v140 offset:2048
	ds_read_b128 v[192:195], v140 offset:3072
	v_lshl_add_u64 v[164:165], s[6:7], 0, v[138:139]
	s_add_i32 m0, s3, 0xc000
	ds_read_b128 v[196:199], v154
	ds_read_b128 v[200:203], v154 offset:1024
	ds_read_b128 v[204:207], v154 offset:2048
	ds_read_b128 v[208:211], v154 offset:3072
	ds_read_b128 v[212:215], v154 offset:4096
	ds_read_b128 v[216:219], v154 offset:5120
	ds_read_b128 v[220:223], v154 offset:6144
	ds_read_b128 v[224:227], v154 offset:7168
	global_load_lds_dwordx4 v[164:165], off
	v_lshl_add_u64 v[164:165], s[6:7], 0, v[136:137]
	s_add_i32 m0, s3, 0xe000
	s_nop 0
	global_load_lds_dwordx4 v[164:165], off
	s_waitcnt vmcnt(8)
	s_waitcnt lgkmcnt(0)
	s_barrier
	s_waitcnt lgkmcnt(0)
	v_mfma_f32_16x16x32_bf16 v[126:129], v[156:159], v[196:199], 0
	v_mfma_f32_16x16x32_bf16 v[122:125], v[172:175], v[196:199], 0
	v_mfma_f32_16x16x32_bf16 v[110:113], v[156:159], v[204:207], 0
	v_mfma_f32_16x16x32_bf16 v[106:109], v[172:175], v[204:207], 0
	v_mfma_f32_16x16x32_bf16 v[94:97], v[156:159], v[212:215], 0
	v_mfma_f32_16x16x32_bf16 v[90:93], v[172:175], v[212:215], 0
	v_mfma_f32_16x16x32_bf16 v[78:81], v[156:159], v[220:223], 0
	v_mfma_f32_16x16x32_bf16 v[74:77], v[172:175], v[220:223], 0
	v_mfma_f32_16x16x32_bf16 v[126:129], v[160:163], v[200:203], v[126:129]
	v_mfma_f32_16x16x32_bf16 v[122:125], v[176:179], v[200:203], v[122:125]
	v_mfma_f32_16x16x32_bf16 v[110:113], v[160:163], v[208:211], v[110:113]
	v_mfma_f32_16x16x32_bf16 v[106:109], v[176:179], v[208:211], v[106:109]
	v_mfma_f32_16x16x32_bf16 v[94:97], v[160:163], v[216:219], v[94:97]
	v_mfma_f32_16x16x32_bf16 v[90:93], v[176:179], v[216:219], v[90:93]
	v_mfma_f32_16x16x32_bf16 v[78:81], v[160:163], v[224:227], v[78:81]
	v_mfma_f32_16x16x32_bf16 v[74:77], v[176:179], v[224:227], v[74:77]
	v_mfma_f32_16x16x32_bf16 v[118:121], v[180:183], v[196:199], 0
	v_mfma_f32_16x16x32_bf16 v[114:117], v[188:191], v[196:199], 0
	v_mfma_f32_16x16x32_bf16 v[102:105], v[180:183], v[204:207], 0
	v_mfma_f32_16x16x32_bf16 v[98:101], v[188:191], v[204:207], 0
	v_mfma_f32_16x16x32_bf16 v[86:89], v[180:183], v[212:215], 0
	v_mfma_f32_16x16x32_bf16 v[82:85], v[188:191], v[212:215], 0
	v_mfma_f32_16x16x32_bf16 v[70:73], v[180:183], v[220:223], 0
	v_mfma_f32_16x16x32_bf16 v[66:69], v[188:191], v[220:223], 0
	v_mfma_f32_16x16x32_bf16 v[118:121], v[184:187], v[200:203], v[118:121]
	v_mfma_f32_16x16x32_bf16 v[114:117], v[192:195], v[200:203], v[114:117]
	v_mfma_f32_16x16x32_bf16 v[102:105], v[184:187], v[208:211], v[102:105]
	v_mfma_f32_16x16x32_bf16 v[98:101], v[192:195], v[208:211], v[98:101]
	v_mfma_f32_16x16x32_bf16 v[86:89], v[184:187], v[216:219], v[86:89]
	v_mfma_f32_16x16x32_bf16 v[82:85], v[192:195], v[216:219], v[82:85]
	v_mfma_f32_16x16x32_bf16 v[70:73], v[184:187], v[224:227], v[70:73]
	v_mfma_f32_16x16x32_bf16 v[66:69], v[192:195], v[224:227], v[66:69]
	s_barrier
	s_add_i32 s27, s27, s0
	v_lshl_add_u64 v[164:165], s[34:35], 0, v[166:167]
	s_mov_b32 m0, s27
	ds_read_b128 v[196:199], v154 offset:16384
	ds_read_b128 v[200:203], v154 offset:17408
	ds_read_b128 v[204:207], v154 offset:18432
	ds_read_b128 v[208:211], v154 offset:19456
	ds_read_b128 v[212:215], v154 offset:20480
	ds_read_b128 v[216:219], v154 offset:21504
	ds_read_b128 v[220:223], v154 offset:22528
	ds_read_b128 v[224:227], v154 offset:23552
	global_load_lds_dwordx4 v[164:165], off
	s_add_i32 m0, s27, 0x2000
	v_lshl_add_u64 v[168:169], s[34:35], 0, v[130:131]
	s_add_u32 s34, s34, s58
	s_addc_u32 s35, s35, s59
	s_add_i32 s11, s11, s0
	global_load_lds_dwordx4 v[168:169], off
	v_lshl_add_u64 v[170:171], s[34:35], 0, v[166:167]
	s_mov_b32 m0, s11
	v_lshl_add_u64 v[228:229], s[34:35], 0, v[130:131]
	global_load_lds_dwordx4 v[170:171], off
	s_add_i32 m0, s11, 0x2000
	v_lshl_add_u64 v[230:231], s[8:9], 0, v[134:135]
	global_load_lds_dwordx4 v[228:229], off
	s_mov_b32 m0, s3
	v_lshl_add_u64 v[232:233], s[8:9], 0, v[132:133]
	global_load_lds_dwordx4 v[230:231], off
	s_mov_b32 m0, s12
	s_nop 0
	global_load_lds_dwordx4 v[232:233], off
	s_waitcnt vmcnt(8)
	s_waitcnt lgkmcnt(0)
	s_barrier
; #define PG8_STAGE(bufoff, gbase, voff) do { _Pragma("unroll") for (int _i = 0; _i < 2; ++_i) \
;         __builtin_amdgcn_global_load_lds((const unsigned*)((const char*)(gbase) + (voff)[_i]), (PG8_LAS unsigned*)(lds + (bufoff) + ldsw + _i * 8192), 16, 0, 0); } while (0)
; #define PG8_LDA(dst, b, h) do { _Pragma("unroll") for (int m = 0; m < 4; ++m) _Pragma("unroll") for (int k = 0; k < 2; ++k) dst[m][k] = *(const PG8_LAS bf16x8*)(lds + PG8_SA(b, h) + aoff + m * 2048 + k * 1024); } while (0)
; #define PG8_LDB(dst, b, h) do { _Pragma("unroll") for (int n = 0; n < 2; ++n) _Pragma("unroll") for (int k = 0; k < 2; ++k) dst[n][k] = *(const PG8_LAS bf16x8*)(lds + PG8_SB(b, h) + boff + n * 2048 + k * 1024); } while (0)
; #define PG8_MMA(ai, bj, At, Bt) do { __builtin_amdgcn_s_setprio(1); _Pragma("unroll") for (int m = 0; m < 4; ++m) _Pragma("unroll") for (int n = 0; n < 2; ++n) _Pragma("unroll") for (int k = 0; k < 2; ++k) \
;         acc[ai][bj][m][n] = __builtin_amdgcn_mfma_f32_16x16x32_bf16(Bt[n][k], At[m][k], acc[ai][bj][m][n], 0, 0, 0); __builtin_amdgcn_s_setprio(0); } while (0)
; #define PG8_WAIT_V(n) asm volatile("s_waitcnt vmcnt(" #n ")" ::: "memory")
; #define PG8_WAIT_L(n) asm volatile("s_waitcnt lgkmcnt(" #n ")" ::: "memory")
; #define PG8_BAR __builtin_amdgcn_s_barrier()
; #define PG8_SCHED __builtin_amdgcn_sched_barrier(0)
;     ...
;             PG8_LDB(B0, 0, 0); PG8_LDB(B1, 0, 1); PG8_SCHED; PG8_LDA(At, 0, 0); PG8_STAGE(PG8_SA(1, 1), a1 + hstepA, voffA);
;             PG8_WAIT_V(8); PG8_WAIT_L(0); PG8_BAR; PG8_MMA(0, 0, At, B0); PG8_MMA(0, 1, At, B1); PG8_BAR; PG8_SCHED;
;             PG8_LDA(At, 0, 1); PG8_STAGE(PG8_SB(0, 0), b2, voffB); PG8_STAGE(PG8_SB(0, 1), b2 + hstepB, voffB); PG8_STAGE(PG8_SA(0, 0), a2, voffA);
;             PG8_WAIT_V(8); PG8_WAIT_L(0); PG8_BAR; PG8_MMA(1, 0, At, B0); PG8_MMA(1, 1, At, B1); PG8_BAR; PG8_SCHED;
;             PG8_LDB(B0, 1, 0); PG8_LDB(B1, 1, 1); PG8_SCHED; PG8_LDA(At, 1, 0); PG8_STAGE(PG8_SA(0, 1), a2 + hstepA, voffA);
;             PG8_WAIT_V(8); PG8_WAIT_L(0); PG8_BAR; PG8_MMA(0, 0, At, B0); PG8_MMA(0, 1, At, B1); PG8_BAR; PG8_SCHED;
;             PG8_LDA(At, 1, 1); PG8_STAGE(PG8_SB(1, 0), b3, voffB); PG8_STAGE(PG8_SB(1, 1), b3 + hstepB, voffB); PG8_STAGE(PG8_SA(1, 0), a3, voffA);
;             PG8_WAIT_V(8); PG8_WAIT_L(0); PG8_BAR; PG8_MMA(1, 0, At, B0); PG8_MMA(1, 1, At, B1); PG8_BAR; PG8_SCHED;
	s_waitcnt lgkmcnt(0)
	v_mfma_f32_16x16x32_bf16 v[62:65], v[156:159], v[196:199], 0
	v_mfma_f32_16x16x32_bf16 v[58:61], v[172:175], v[196:199], 0
	v_mfma_f32_16x16x32_bf16 v[46:49], v[156:159], v[204:207], 0
	v_mfma_f32_16x16x32_bf16 v[42:45], v[172:175], v[204:207], 0
	v_mfma_f32_16x16x32_bf16 v[30:33], v[156:159], v[212:215], 0
	v_mfma_f32_16x16x32_bf16 v[26:29], v[172:175], v[212:215], 0
	v_mfma_f32_16x16x32_bf16 v[14:17], v[156:159], v[220:223], 0
	v_mfma_f32_16x16x32_bf16 v[10:13], v[172:175], v[220:223], 0
	v_mfma_f32_16x16x32_bf16 v[62:65], v[160:163], v[200:203], v[62:65]
	v_mfma_f32_16x16x32_bf16 v[58:61], v[176:179], v[200:203], v[58:61]
	v_mfma_f32_16x16x32_bf16 v[46:49], v[160:163], v[208:211], v[46:49]
	v_mfma_f32_16x16x32_bf16 v[42:45], v[176:179], v[208:211], v[42:45]
	v_mfma_f32_16x16x32_bf16 v[30:33], v[160:163], v[216:219], v[30:33]
	v_mfma_f32_16x16x32_bf16 v[26:29], v[176:179], v[216:219], v[26:29]
	v_mfma_f32_16x16x32_bf16 v[14:17], v[160:163], v[224:227], v[14:17]
	v_mfma_f32_16x16x32_bf16 v[10:13], v[176:179], v[224:227], v[10:13]
	v_mfma_f32_16x16x32_bf16 v[54:57], v[180:183], v[196:199], 0
	v_mfma_f32_16x16x32_bf16 v[50:53], v[188:191], v[196:199], 0
	v_mfma_f32_16x16x32_bf16 v[38:41], v[180:183], v[204:207], 0
	v_mfma_f32_16x16x32_bf16 v[34:37], v[188:191], v[204:207], 0
	v_mfma_f32_16x16x32_bf16 v[22:25], v[180:183], v[212:215], 0
	v_mfma_f32_16x16x32_bf16 v[18:21], v[188:191], v[212:215], 0
	v_mfma_f32_16x16x32_bf16 v[6:9], v[180:183], v[220:223], 0
	v_mfma_f32_16x16x32_bf16 v[2:5], v[188:191], v[220:223], 0
	v_mfma_f32_16x16x32_bf16 v[54:57], v[184:187], v[200:203], v[54:57]
	v_mfma_f32_16x16x32_bf16 v[50:53], v[192:195], v[200:203], v[50:53]
	v_mfma_f32_16x16x32_bf16 v[38:41], v[184:187], v[208:211], v[38:41]
	v_mfma_f32_16x16x32_bf16 v[34:37], v[192:195], v[208:211], v[34:37]
	v_mfma_f32_16x16x32_bf16 v[22:25], v[184:187], v[216:219], v[22:25]
	v_mfma_f32_16x16x32_bf16 v[18:21], v[192:195], v[216:219], v[18:21]
	v_mfma_f32_16x16x32_bf16 v[6:9], v[184:187], v[224:227], v[6:9]
	v_mfma_f32_16x16x32_bf16 v[2:5], v[192:195], v[224:227], v[2:5]
	s_barrier
	s_add_i32 s11, 0, 0x18000
	v_add_u32_e32 v140, s11, v151
	s_add_i32 s27, 0, 0x1c000
	ds_read_b128 v[156:159], v140
	ds_read_b128 v[160:163], v140 offset:1024
	ds_read_b128 v[172:175], v140 offset:2048
	ds_read_b128 v[176:179], v140 offset:3072
	v_add_u32_e32 v140, s27, v151
	ds_read_b128 v[180:183], v140
	ds_read_b128 v[184:187], v140 offset:1024
	ds_read_b128 v[188:191], v140 offset:2048
	ds_read_b128 v[192:195], v140 offset:3072
	s_add_u32 s8, s8, s58
	s_addc_u32 s9, s9, s59
	s_mov_b32 m0, s13
	v_lshl_add_u64 v[234:235], s[8:9], 0, v[134:135]
	ds_read_b128 v[196:199], v154 offset:32768
	ds_read_b128 v[200:203], v154 offset:33792
	ds_read_b128 v[204:207], v154 offset:34816
	ds_read_b128 v[208:211], v154 offset:35840
	ds_read_b128 v[212:215], v154 offset:36864
	ds_read_b128 v[216:219], v154 offset:37888
	ds_read_b128 v[220:223], v154 offset:38912
	ds_read_b128 v[224:227], v154 offset:39936
	global_load_lds_dwordx4 v[234:235], off
	v_lshl_add_u64 v[234:235], s[8:9], 0, v[132:133]
	s_mov_b32 m0, s14
	s_nop 0
	global_load_lds_dwordx4 v[234:235], off
	s_waitcnt vmcnt(8)
	s_waitcnt lgkmcnt(0)
	s_barrier
	s_waitcnt lgkmcnt(0)
	v_mfma_f32_16x16x32_bf16 v[126:129], v[156:159], v[196:199], v[126:129]
	v_mfma_f32_16x16x32_bf16 v[122:125], v[172:175], v[196:199], v[122:125]
	v_mfma_f32_16x16x32_bf16 v[110:113], v[156:159], v[204:207], v[110:113]
	v_mfma_f32_16x16x32_bf16 v[106:109], v[172:175], v[204:207], v[106:109]
	v_mfma_f32_16x16x32_bf16 v[94:97], v[156:159], v[212:215], v[94:97]
	v_mfma_f32_16x16x32_bf16 v[90:93], v[172:175], v[212:215], v[90:93]
	v_mfma_f32_16x16x32_bf16 v[78:81], v[156:159], v[220:223], v[78:81]
	v_mfma_f32_16x16x32_bf16 v[74:77], v[172:175], v[220:223], v[74:77]
	v_mfma_f32_16x16x32_bf16 v[126:129], v[160:163], v[200:203], v[126:129]
	v_mfma_f32_16x16x32_bf16 v[122:125], v[176:179], v[200:203], v[122:125]
	v_mfma_f32_16x16x32_bf16 v[110:113], v[160:163], v[208:211], v[110:113]
	v_mfma_f32_16x16x32_bf16 v[106:109], v[176:179], v[208:211], v[106:109]
	v_mfma_f32_16x16x32_bf16 v[94:97], v[160:163], v[216:219], v[94:97]
	v_mfma_f32_16x16x32_bf16 v[90:93], v[176:179], v[216:219], v[90:93]
	v_mfma_f32_16x16x32_bf16 v[78:81], v[160:163], v[224:227], v[78:81]
	v_mfma_f32_16x16x32_bf16 v[74:77], v[176:179], v[224:227], v[74:77]
	v_mfma_f32_16x16x32_bf16 v[118:121], v[180:183], v[196:199], v[118:121]
	v_mfma_f32_16x16x32_bf16 v[114:117], v[188:191], v[196:199], v[114:117]
	v_mfma_f32_16x16x32_bf16 v[102:105], v[180:183], v[204:207], v[102:105]
	v_mfma_f32_16x16x32_bf16 v[98:101], v[188:191], v[204:207], v[98:101]
	v_mfma_f32_16x16x32_bf16 v[86:89], v[180:183], v[212:215], v[86:89]
	v_mfma_f32_16x16x32_bf16 v[82:85], v[188:191], v[212:215], v[82:85]
	v_mfma_f32_16x16x32_bf16 v[70:73], v[180:183], v[220:223], v[70:73]
	v_mfma_f32_16x16x32_bf16 v[66:69], v[188:191], v[220:223], v[66:69]
	v_mfma_f32_16x16x32_bf16 v[118:121], v[184:187], v[200:203], v[118:121]
	v_mfma_f32_16x16x32_bf16 v[114:117], v[192:195], v[200:203], v[114:117]
	v_mfma_f32_16x16x32_bf16 v[102:105], v[184:187], v[208:211], v[102:105]
	v_mfma_f32_16x16x32_bf16 v[98:101], v[192:195], v[208:211], v[98:101]
	v_mfma_f32_16x16x32_bf16 v[86:89], v[184:187], v[216:219], v[86:89]
	v_mfma_f32_16x16x32_bf16 v[82:85], v[192:195], v[216:219], v[82:85]
	v_mfma_f32_16x16x32_bf16 v[70:73], v[184:187], v[224:227], v[70:73]
	v_mfma_f32_16x16x32_bf16 v[66:69], v[192:195], v[224:227], v[66:69]
	s_barrier
; #define PG8_STAGE(bufoff, gbase, voff) do { _Pragma("unroll") for (int _i = 0; _i < 2; ++_i) \
;         __builtin_amdgcn_global_load_lds((const unsigned*)((const char*)(gbase) + (voff)[_i]), (PG8_LAS unsigned*)(lds + (bufoff) + ldsw + _i * 8192), 16, 0, 0); } while (0)
; #define PG8_LDA(dst, b, h) do { _Pragma("unroll") for (int m = 0; m < 4; ++m) _Pragma("unroll") for (int k = 0; k < 2; ++k) dst[m][k] = *(const PG8_LAS bf16x8*)(lds + PG8_SA(b, h) + aoff + m * 2048 + k * 1024); } while (0)
; #define PG8_MMA(ai, bj, At, Bt) do { __builtin_amdgcn_s_setprio(1); _Pragma("unroll") for (int m = 0; m < 4; ++m) _Pragma("unroll") for (int n = 0; n < 2; ++n) _Pragma("unroll") for (int k = 0; k < 2; ++k) \
;         acc[ai][bj][m][n] = __builtin_amdgcn_mfma_f32_16x16x32_bf16(Bt[n][k], At[m][k], acc[ai][bj][m][n], 0, 0, 0); __builtin_amdgcn_s_setprio(0); } while (0)
; #define PG8_WAIT_V(n) asm volatile("s_waitcnt vmcnt(" #n ")" ::: "memory")
; #define PG8_WAIT_L(n) asm volatile("s_waitcnt lgkmcnt(" #n ")" ::: "memory")
; #define PG8_BAR __builtin_amdgcn_s_barrier()
; #define PG8_SCHED __builtin_amdgcn_sched_barrier(0)
;     ...
;         for (int t = 0; t < nt; t += 2) {
;             const bool last = (t == nt - 2);
;             const char* a1 = cA + (size_t)(t + 1) * kstep;
;             const char* a2 = last ? nA : cA + (size_t)(t + 2) * kstep; const char* b2 = last ? nB : cB + (size_t)(t + 2) * kstep;
;             const char* a3 = a2 + kstep; const char* b3 = b2 + kstep;
;     ...
;             PG8_LDA(At, 1, 1); PG8_STAGE(PG8_SB(1, 0), b3, voffB); PG8_STAGE(PG8_SB(1, 1), b3 + hstepB, voffB); PG8_STAGE(PG8_SA(1, 0), a3, voffA);
;             PG8_WAIT_V(8); PG8_WAIT_L(0); PG8_BAR; PG8_MMA(1, 0, At, B0); PG8_MMA(1, 1, At, B1); PG8_BAR; PG8_SCHED;
	s_add_i32 s8, s11, s0
	v_lshl_add_u64 v[164:165], v[164:165], 0, s[62:63]
	s_mov_b32 m0, s8
	ds_read_b128 v[196:199], v154 offset:49152
	ds_read_b128 v[200:203], v154 offset:50176
	ds_read_b128 v[204:207], v154 offset:51200
	ds_read_b128 v[208:211], v154 offset:52224
	ds_read_b128 v[212:215], v154 offset:53248
	ds_read_b128 v[216:219], v154 offset:54272
	ds_read_b128 v[220:223], v154 offset:55296
	ds_read_b128 v[224:227], v154 offset:56320
	global_load_lds_dwordx4 v[164:165], off
	v_lshl_add_u64 v[164:165], v[168:169], 0, s[62:63]
	s_add_i32 m0, s8, 0x2000
	s_add_i32 s8, s27, s0
	global_load_lds_dwordx4 v[164:165], off
	v_lshl_add_u64 v[164:165], v[170:171], 0, s[62:63]
	s_mov_b32 m0, s8
	s_nop 0
	global_load_lds_dwordx4 v[164:165], off
	v_lshl_add_u64 v[164:165], v[228:229], 0, s[62:63]
	s_add_i32 m0, s8, 0x2000
	s_nop 0
	global_load_lds_dwordx4 v[164:165], off
	v_lshl_add_u64 v[164:165], v[230:231], 0, s[62:63]
	s_mov_b32 m0, s16
	s_nop 0
	global_load_lds_dwordx4 v[164:165], off
	v_lshl_add_u64 v[164:165], v[232:233], 0, s[62:63]
	s_mov_b32 m0, s17
	s_nop 0
	global_load_lds_dwordx4 v[164:165], off
	s_waitcnt vmcnt(8)
	s_waitcnt lgkmcnt(0)
	s_barrier
	s_waitcnt lgkmcnt(0)
	v_mfma_f32_16x16x32_bf16 v[62:65], v[156:159], v[196:199], v[62:65]
	v_mfma_f32_16x16x32_bf16 v[58:61], v[172:175], v[196:199], v[58:61]
	v_mfma_f32_16x16x32_bf16 v[46:49], v[156:159], v[204:207], v[46:49]
	v_mfma_f32_16x16x32_bf16 v[42:45], v[172:175], v[204:207], v[42:45]
	v_mfma_f32_16x16x32_bf16 v[30:33], v[156:159], v[212:215], v[30:33]
	v_mfma_f32_16x16x32_bf16 v[26:29], v[172:175], v[212:215], v[26:29]
	v_mfma_f32_16x16x32_bf16 v[14:17], v[156:159], v[220:223], v[14:17]
	v_mfma_f32_16x16x32_bf16 v[10:13], v[172:175], v[220:223], v[10:13]
	v_mfma_f32_16x16x32_bf16 v[62:65], v[160:163], v[200:203], v[62:65]
	v_mfma_f32_16x16x32_bf16 v[58:61], v[176:179], v[200:203], v[58:61]
	v_mfma_f32_16x16x32_bf16 v[46:49], v[160:163], v[208:211], v[46:49]
	v_mfma_f32_16x16x32_bf16 v[42:45], v[176:179], v[208:211], v[42:45]
	v_mfma_f32_16x16x32_bf16 v[30:33], v[160:163], v[216:219], v[30:33]
	v_mfma_f32_16x16x32_bf16 v[26:29], v[176:179], v[216:219], v[26:29]
	v_mfma_f32_16x16x32_bf16 v[14:17], v[160:163], v[224:227], v[14:17]
	v_mfma_f32_16x16x32_bf16 v[10:13], v[176:179], v[224:227], v[10:13]
	v_mfma_f32_16x16x32_bf16 v[54:57], v[180:183], v[196:199], v[54:57]
	v_mfma_f32_16x16x32_bf16 v[50:53], v[188:191], v[196:199], v[50:53]
	v_mfma_f32_16x16x32_bf16 v[38:41], v[180:183], v[204:207], v[38:41]
	v_mfma_f32_16x16x32_bf16 v[34:37], v[188:191], v[204:207], v[34:37]
	v_mfma_f32_16x16x32_bf16 v[22:25], v[180:183], v[212:215], v[22:25]
	v_mfma_f32_16x16x32_bf16 v[18:21], v[188:191], v[212:215], v[18:21]
	v_mfma_f32_16x16x32_bf16 v[6:9], v[180:183], v[220:223], v[6:9]
	v_mfma_f32_16x16x32_bf16 v[2:5], v[188:191], v[220:223], v[2:5]
	v_mfma_f32_16x16x32_bf16 v[54:57], v[184:187], v[200:203], v[54:57]
	v_mfma_f32_16x16x32_bf16 v[50:53], v[192:195], v[200:203], v[50:53]
	v_mfma_f32_16x16x32_bf16 v[38:41], v[184:187], v[208:211], v[38:41]
	v_mfma_f32_16x16x32_bf16 v[34:37], v[192:195], v[208:211], v[34:37]
	v_mfma_f32_16x16x32_bf16 v[22:25], v[184:187], v[216:219], v[22:25]
	v_mfma_f32_16x16x32_bf16 v[18:21], v[192:195], v[216:219], v[18:21]
	v_mfma_f32_16x16x32_bf16 v[6:9], v[184:187], v[224:227], v[6:9]
	v_mfma_f32_16x16x32_bf16 v[2:5], v[192:195], v[224:227], v[2:5]
	s_barrier
	s_add_u32 s24, s24, 0x100
	s_addc_u32 s25, s25, 0
	s_add_u32 s6, s6, 0x100
	s_addc_u32 s7, s7, 0
	s_cmp_ge_i32 s10, s15
	s_mov_b32 s8, s10
	s_cbranch_scc1 .LBB0_614

; __device__ __forceinline__ unsigned cvt_pk_bf16(float lo, float hi) { f32x2_t v = {lo, hi}; bf16x2_t b = __builtin_convertvector(v, bf16x2_t); return __builtin_bit_cast(unsigned, b); }
; __device__ __forceinline__ float silu_mul(float a, float b) { return a * b * __builtin_amdgcn_rcpf(1.0f + __builtin_amdgcn_exp2f(a * -1.4426950408889634f)); }
;     __device__ __forceinline__ void operator()(const f32x4 (&acc)[2][2][4][2], const Unit& u, int wr, int wc, int fr, int fq, const float (&rr)[2][4]) const {
;         const int row0 = u.pm * BM + wr * 64 + fr, col0 = u.pn * 128 + wc * 32 + 8 * fq;
; #pragma unroll
;         for (int ai = 0; ai < 2; ++ai)
; #pragma unroll
;             for (int m = 0; m < 4; ++m) { const int row = row0 + ai * HALF + m * 16; const float r = rr[ai][m];
;                 const f32x4 g0 = acc[ai][0][m][0] * r, g1 = acc[ai][0][m][1] * r, u0 = acc[ai][1][m][0] * r, u1 = acc[ai][1][m][1] * r;
;                 u32x4 w; w.x = cvt_pk_bf16(silu_mul(g0[0], u0[0]), silu_mul(g0[1], u0[1])); w.y = cvt_pk_bf16(silu_mul(g0[2], u0[2]), silu_mul(g0[3], u0[3]));
;                 w.z = cvt_pk_bf16(silu_mul(g1[0], u1[0]), silu_mul(g1[1], u1[1])); w.w = cvt_pk_bf16(silu_mul(g1[2], u1[2]), silu_mul(g1[3], u1[3]));
;                 *(u32x4*)(O + (size_t)row * ldc + col0) = w; }
.LBB0_616:
	s_lshl_b32 s6, s23, 8
	s_add_i32 s6, s6, s2
	s_movk_i32 s8, 0x1600
	v_and_b32_e32 v155, 24, v153
	v_lshl_or_b32 v155, v155, 1, v141
	v_lshrrev_b32_e32 v150, 2, v155
	v_and_b32_e32 v152, 3, v155
	v_lshrrev_b32_e32 v146, 4, v155
	v_lshrrev_b32_e32 v148, 2, v141
	v_xor_b32_e32 v146, v146, v148
	v_lshlrev_b32_e32 v146, 4, v146
	v_lshl_or_b32 v146, v141, 6, v146
	v_add_u32_e32 v146, s3, v146
	v_add_u32_e32 v146, 0x23000, v146
	v_lshrrev_b32_e32 v148, 2, v150
	v_xor_b32_e32 v148, v148, v152
	v_lshlrev_b32_e32 v148, 4, v148
	v_lshl_or_b32 v148, v150, 6, v148
	v_add_u32_e32 v148, s3, v148
	v_add_u32_e32 v148, 0x23000, v148
	v_add_u32_e32 v150, s6, v150
	v_mul_lo_u32 v150, v150, s8
	v_and_b32_e32 v158, 0x60, v153
	v_lshl_or_b32 v158, s22, 7, v158
	v_lshlrev_b32_e32 v158, 1, v158
	v_lshl_or_b32 v158, v152, 4, v158
	v_mov_b32_e32 v159, 0
	v_add_u32_e32 v158, v158, v150
	v_mov_b32_e32 v156, 1.0
	v_mov_b32_e32 v157, 1.0
	v_lshl_add_u64 v[158:159], s[56:57], 0, v[158:159]
	v_mov_b32_e32 v244, v158
	v_mov_b32_e32 v245, v159
	s_bitcmp1_b32 s101, 1
	s_cbranch_scc1 .Lepi_h1
	v_cvt_f32_f16_e32 v140, v143
	v_pk_mul_f32 v[118:119], v[126:127], v[118:119]
	v_pk_mul_f32 v[120:121], v[128:129], v[120:121]
	v_pk_mul_f32 v[114:115], v[122:123], v[114:115]
	v_pk_mul_f32 v[116:117], v[124:125], v[116:117]
	v_mul_f32_e32 v142, 0xbfb8aa3b, v140
	v_mul_f32_e32 v144, v140, v140
	v_pk_mul_f32 v[126:127], v[126:127], v[142:143] op_sel_hi:[1,0]
	v_pk_mul_f32 v[128:129], v[128:129], v[142:143] op_sel_hi:[1,0]
	v_pk_mul_f32 v[122:123], v[122:123], v[142:143] op_sel_hi:[1,0]
	v_pk_mul_f32 v[124:125], v[124:125], v[142:143] op_sel_hi:[1,0]
	v_exp_f32_e32 v126, v126
	v_exp_f32_e32 v127, v127
	v_exp_f32_e32 v128, v128
	v_exp_f32_e32 v129, v129
	v_exp_f32_e32 v122, v122
	v_exp_f32_e32 v123, v123
	v_exp_f32_e32 v124, v124
	v_exp_f32_e32 v125, v125
	v_pk_mul_f32 v[118:119], v[118:119], v[144:145] op_sel_hi:[1,0]
	v_pk_mul_f32 v[120:121], v[120:121], v[144:145] op_sel_hi:[1,0]
	v_pk_mul_f32 v[114:115], v[114:115], v[144:145] op_sel_hi:[1,0]
	v_pk_mul_f32 v[116:117], v[116:117], v[144:145] op_sel_hi:[1,0]
	v_pk_add_f32 v[126:127], v[126:127], v[156:157]
	v_pk_add_f32 v[128:129], v[128:129], v[156:157]
	v_pk_add_f32 v[122:123], v[122:123], v[156:157]
	v_pk_add_f32 v[124:125], v[124:125], v[156:157]
	v_rcp_f32_e32 v126, v126
	v_rcp_f32_e32 v127, v127
	v_rcp_f32_e32 v128, v128
	v_rcp_f32_e32 v129, v129
	v_rcp_f32_e32 v122, v122
	v_rcp_f32_e32 v123, v123
	v_rcp_f32_e32 v124, v124
	v_rcp_f32_e32 v125, v125
	s_nop 0
	v_pk_mul_f32 v[118:119], v[118:119], v[126:127]
	v_pk_mul_f32 v[120:121], v[120:121], v[128:129]
	v_pk_mul_f32 v[114:115], v[114:115], v[122:123]
	v_pk_mul_f32 v[116:117], v[116:117], v[124:125]
	v_cvt_pk_bf16_f32 v118, v118, v119
	v_cvt_pk_bf16_f32 v119, v120, v121
	v_cvt_pk_bf16_f32 v120, v114, v115
	v_cvt_pk_bf16_f32 v121, v116, v117
	ds_write_b128 v146, v[118:121]
	ds_read_b128 v[126:129], v148
	v_cvt_f32_f16_e32 v140, v145
	v_pk_mul_f32 v[102:103], v[110:111], v[102:103]
	v_pk_mul_f32 v[104:105], v[112:113], v[104:105]
	v_pk_mul_f32 v[98:99], v[106:107], v[98:99]
	v_pk_mul_f32 v[100:101], v[108:109], v[100:101]
	v_mul_f32_e32 v142, 0xbfb8aa3b, v140
	v_mul_f32_e32 v144, v140, v140
	v_pk_mul_f32 v[110:111], v[110:111], v[142:143] op_sel_hi:[1,0]
	v_pk_mul_f32 v[112:113], v[112:113], v[142:143] op_sel_hi:[1,0]
	v_pk_mul_f32 v[106:107], v[106:107], v[142:143] op_sel_hi:[1,0]
	v_pk_mul_f32 v[108:109], v[108:109], v[142:143] op_sel_hi:[1,0]
	v_exp_f32_e32 v110, v110
	v_exp_f32_e32 v111, v111
	v_exp_f32_e32 v112, v112
	v_exp_f32_e32 v113, v113
	v_exp_f32_e32 v106, v106
	v_exp_f32_e32 v107, v107
	v_exp_f32_e32 v108, v108
	v_exp_f32_e32 v109, v109
	v_pk_mul_f32 v[102:103], v[102:103], v[144:145] op_sel_hi:[1,0]
	v_pk_mul_f32 v[104:105], v[104:105], v[144:145] op_sel_hi:[1,0]
	v_pk_mul_f32 v[98:99], v[98:99], v[144:145] op_sel_hi:[1,0]
	v_pk_mul_f32 v[100:101], v[100:101], v[144:145] op_sel_hi:[1,0]
	v_pk_add_f32 v[110:111], v[110:111], v[156:157]
	v_pk_add_f32 v[112:113], v[112:113], v[156:157]
	v_pk_add_f32 v[106:107], v[106:107], v[156:157]
	v_pk_add_f32 v[108:109], v[108:109], v[156:157]
	v_rcp_f32_e32 v110, v110
	v_rcp_f32_e32 v111, v111
	v_rcp_f32_e32 v112, v112
	v_rcp_f32_e32 v113, v113
	v_rcp_f32_e32 v106, v106
	v_rcp_f32_e32 v107, v107
	v_rcp_f32_e32 v108, v108
	v_rcp_f32_e32 v109, v109
	s_waitcnt lgkmcnt(0)
	global_store_dwordx4 v[158:159], v[126:129], off
	v_pk_mul_f32 v[102:103], v[102:103], v[110:111]
	v_pk_mul_f32 v[104:105], v[104:105], v[112:113]
	v_pk_mul_f32 v[98:99], v[98:99], v[106:107]
	v_pk_mul_f32 v[100:101], v[100:101], v[108:109]
	v_cvt_pk_bf16_f32 v102, v102, v103
	v_cvt_pk_bf16_f32 v103, v104, v105
	v_cvt_pk_bf16_f32 v104, v98, v99
	v_cvt_pk_bf16_f32 v105, v100, v101
	ds_write_b128 v146, v[102:105]
	ds_read_b128 v[110:113], v148
	v_cvt_f32_f16_e32 v140, v147
	v_pk_mul_f32 v[86:87], v[94:95], v[86:87]
	v_pk_mul_f32 v[88:89], v[96:97], v[88:89]
	v_pk_mul_f32 v[82:83], v[90:91], v[82:83]
	v_pk_mul_f32 v[84:85], v[92:93], v[84:85]
	v_mul_f32_e32 v142, 0xbfb8aa3b, v140
	v_mul_f32_e32 v144, v140, v140
	v_pk_mul_f32 v[94:95], v[94:95], v[142:143] op_sel_hi:[1,0]
	v_pk_mul_f32 v[96:97], v[96:97], v[142:143] op_sel_hi:[1,0]
	v_pk_mul_f32 v[90:91], v[90:91], v[142:143] op_sel_hi:[1,0]
	v_pk_mul_f32 v[92:93], v[92:93], v[142:143] op_sel_hi:[1,0]
	v_exp_f32_e32 v94, v94
	v_exp_f32_e32 v95, v95
	v_exp_f32_e32 v96, v96
	v_exp_f32_e32 v97, v97
	v_exp_f32_e32 v90, v90
	v_exp_f32_e32 v91, v91
	v_exp_f32_e32 v92, v92
	v_exp_f32_e32 v93, v93
	v_pk_mul_f32 v[86:87], v[86:87], v[144:145] op_sel_hi:[1,0]
	v_pk_mul_f32 v[88:89], v[88:89], v[144:145] op_sel_hi:[1,0]
	v_pk_mul_f32 v[82:83], v[82:83], v[144:145] op_sel_hi:[1,0]
	v_pk_mul_f32 v[84:85], v[84:85], v[144:145] op_sel_hi:[1,0]
	v_pk_add_f32 v[94:95], v[94:95], v[156:157]
	v_pk_add_f32 v[96:97], v[96:97], v[156:157]
	v_pk_add_f32 v[90:91], v[90:91], v[156:157]
	v_pk_add_f32 v[92:93], v[92:93], v[156:157]
	v_rcp_f32_e32 v94, v94
	v_rcp_f32_e32 v95, v95
	v_rcp_f32_e32 v96, v96
	v_rcp_f32_e32 v97, v97
	v_rcp_f32_e32 v90, v90
	v_rcp_f32_e32 v91, v91
	v_rcp_f32_e32 v92, v92
	v_rcp_f32_e32 v93, v93
	s_mov_b64 s[6:7], 0x16000
	v_lshl_add_u64 v[158:159], v[158:159], 0, s[6:7]
	s_waitcnt lgkmcnt(0)
; __device__ __forceinline__ unsigned cvt_pk_bf16(float lo, float hi) { f32x2_t v = {lo, hi}; bf16x2_t b = __builtin_convertvector(v, bf16x2_t); return __builtin_bit_cast(unsigned, b); }
; __device__ __forceinline__ float silu_mul(float a, float b) { return a * b * __builtin_amdgcn_rcpf(1.0f + __builtin_amdgcn_exp2f(a * -1.4426950408889634f)); }
;     __device__ __forceinline__ void operator()(const f32x4 (&acc)[2][2][4][2], const Unit& u, int wr, int wc, int fr, int fq, const float (&rr)[2][4]) const {
;         const int row0 = u.pm * BM + wr * 64 + fr, col0 = u.pn * 128 + wc * 32 + 8 * fq;
; #pragma unroll
;         for (int ai = 0; ai < 2; ++ai)
; #pragma unroll
;             for (int m = 0; m < 4; ++m) { const int row = row0 + ai * HALF + m * 16; const float r = rr[ai][m];
;                 const f32x4 g0 = acc[ai][0][m][0] * r, g1 = acc[ai][0][m][1] * r, u0 = acc[ai][1][m][0] * r, u1 = acc[ai][1][m][1] * r;
;                 u32x4 w; w.x = cvt_pk_bf16(silu_mul(g0[0], u0[0]), silu_mul(g0[1], u0[1])); w.y = cvt_pk_bf16(silu_mul(g0[2], u0[2]), silu_mul(g0[3], u0[3]));
;                 w.z = cvt_pk_bf16(silu_mul(g1[0], u1[0]), silu_mul(g1[1], u1[1])); w.w = cvt_pk_bf16(silu_mul(g1[2], u1[2]), silu_mul(g1[3], u1[3]));
;                 *(u32x4*)(O + (size_t)row * ldc + col0) = w; }
	global_store_dwordx4 v[158:159], v[110:113], off
	v_pk_mul_f32 v[86:87], v[86:87], v[94:95]
	v_pk_mul_f32 v[88:89], v[88:89], v[96:97]
	v_pk_mul_f32 v[82:83], v[82:83], v[90:91]
	v_pk_mul_f32 v[84:85], v[84:85], v[92:93]
	v_cvt_pk_bf16_f32 v86, v86, v87
	v_cvt_pk_bf16_f32 v87, v88, v89
	v_cvt_pk_bf16_f32 v88, v82, v83
	v_cvt_pk_bf16_f32 v89, v84, v85
	ds_write_b128 v146, v[86:89]
	ds_read_b128 v[94:97], v148
	v_cvt_f32_f16_e32 v140, v149
	v_pk_mul_f32 v[70:71], v[78:79], v[70:71]
	v_pk_mul_f32 v[72:73], v[80:81], v[72:73]
	v_pk_mul_f32 v[66:67], v[74:75], v[66:67]
	v_pk_mul_f32 v[68:69], v[76:77], v[68:69]
	v_mul_f32_e32 v142, 0xbfb8aa3b, v140
	v_mul_f32_e32 v144, v140, v140
	v_pk_mul_f32 v[78:79], v[78:79], v[142:143] op_sel_hi:[1,0]
	v_pk_mul_f32 v[80:81], v[80:81], v[142:143] op_sel_hi:[1,0]
	v_pk_mul_f32 v[74:75], v[74:75], v[142:143] op_sel_hi:[1,0]
	v_pk_mul_f32 v[76:77], v[76:77], v[142:143] op_sel_hi:[1,0]
	v_exp_f32_e32 v78, v78
	v_exp_f32_e32 v79, v79
	v_exp_f32_e32 v80, v80
	v_exp_f32_e32 v81, v81
	v_exp_f32_e32 v74, v74
	v_exp_f32_e32 v75, v75
	v_exp_f32_e32 v76, v76
	v_exp_f32_e32 v77, v77
	v_pk_mul_f32 v[70:71], v[70:71], v[144:145] op_sel_hi:[1,0]
	v_pk_mul_f32 v[72:73], v[72:73], v[144:145] op_sel_hi:[1,0]
	v_pk_mul_f32 v[66:67], v[66:67], v[144:145] op_sel_hi:[1,0]
	v_pk_mul_f32 v[68:69], v[68:69], v[144:145] op_sel_hi:[1,0]
	v_pk_add_f32 v[78:79], v[78:79], v[156:157]
	v_pk_add_f32 v[80:81], v[80:81], v[156:157]
	v_pk_add_f32 v[74:75], v[74:75], v[156:157]
	v_pk_add_f32 v[76:77], v[76:77], v[156:157]
	v_rcp_f32_e32 v78, v78
	v_rcp_f32_e32 v79, v79
	v_rcp_f32_e32 v80, v80
	v_rcp_f32_e32 v81, v81
	v_rcp_f32_e32 v74, v74
	v_rcp_f32_e32 v75, v75
	v_rcp_f32_e32 v76, v76
	v_rcp_f32_e32 v77, v77
	s_mov_b64 s[6:7], 0x16000
	v_lshl_add_u64 v[158:159], v[158:159], 0, s[6:7]
	s_waitcnt lgkmcnt(0)
	global_store_dwordx4 v[158:159], v[94:97], off
	v_pk_mul_f32 v[70:71], v[70:71], v[78:79]
	v_pk_mul_f32 v[72:73], v[72:73], v[80:81]
	v_pk_mul_f32 v[66:67], v[66:67], v[74:75]
	v_pk_mul_f32 v[68:69], v[68:69], v[76:77]
	v_cvt_pk_bf16_f32 v70, v70, v71
	v_cvt_pk_bf16_f32 v71, v72, v73
	v_cvt_pk_bf16_f32 v72, v66, v67
	v_cvt_pk_bf16_f32 v73, v68, v69
	ds_write_b128 v146, v[70:73]
	ds_read_b128 v[78:81], v148
	s_mov_b64 s[6:7], 0x16000
	v_lshl_add_u64 v[158:159], v[158:159], 0, s[6:7]
	s_waitcnt lgkmcnt(0)
	global_store_dwordx4 v[158:159], v[78:81], off
.Lepi_h1:
	s_bitcmp1_b32 s101, 0
	s_cbranch_scc1 .Lepi_end
	s_mov_b64 s[6:7], 0xb0000
	v_lshl_add_u64 v[158:159], v[244:245], 0, s[6:7]
	v_cvt_f32_f16_sdwa v140, v143 dst_sel:DWORD dst_unused:UNUSED_PAD src0_sel:WORD_1
	v_pk_mul_f32 v[54:55], v[62:63], v[54:55]
	v_pk_mul_f32 v[56:57], v[64:65], v[56:57]
	v_pk_mul_f32 v[50:51], v[58:59], v[50:51]
	v_pk_mul_f32 v[52:53], v[60:61], v[52:53]
	v_mul_f32_e32 v142, 0xbfb8aa3b, v140
	v_mul_f32_e32 v144, v140, v140
	v_pk_mul_f32 v[62:63], v[62:63], v[142:143] op_sel_hi:[1,0]
	v_pk_mul_f32 v[64:65], v[64:65], v[142:143] op_sel_hi:[1,0]
	v_pk_mul_f32 v[58:59], v[58:59], v[142:143] op_sel_hi:[1,0]
	v_pk_mul_f32 v[60:61], v[60:61], v[142:143] op_sel_hi:[1,0]
	v_exp_f32_e32 v62, v62
	v_exp_f32_e32 v63, v63
	v_exp_f32_e32 v64, v64
	v_exp_f32_e32 v65, v65
	v_exp_f32_e32 v58, v58
	v_exp_f32_e32 v59, v59
	v_exp_f32_e32 v60, v60
	v_exp_f32_e32 v61, v61
	v_pk_mul_f32 v[54:55], v[54:55], v[144:145] op_sel_hi:[1,0]
	v_pk_mul_f32 v[56:57], v[56:57], v[144:145] op_sel_hi:[1,0]
	v_pk_mul_f32 v[50:51], v[50:51], v[144:145] op_sel_hi:[1,0]
	v_pk_mul_f32 v[52:53], v[52:53], v[144:145] op_sel_hi:[1,0]
	v_pk_add_f32 v[62:63], v[62:63], v[156:157]
	v_pk_add_f32 v[64:65], v[64:65], v[156:157]
	v_pk_add_f32 v[58:59], v[58:59], v[156:157]
	v_pk_add_f32 v[60:61], v[60:61], v[156:157]
	v_rcp_f32_e32 v62, v62
	v_rcp_f32_e32 v63, v63
	v_rcp_f32_e32 v64, v64
	v_rcp_f32_e32 v65, v65
	v_rcp_f32_e32 v58, v58
	v_rcp_f32_e32 v59, v59
	v_rcp_f32_e32 v60, v60
	v_rcp_f32_e32 v61, v61
	s_nop 0
	v_pk_mul_f32 v[54:55], v[54:55], v[62:63]
	v_pk_mul_f32 v[56:57], v[56:57], v[64:65]
	v_pk_mul_f32 v[50:51], v[50:51], v[58:59]
	v_pk_mul_f32 v[52:53], v[52:53], v[60:61]
	v_cvt_pk_bf16_f32 v54, v54, v55
	v_cvt_pk_bf16_f32 v55, v56, v57
	v_cvt_pk_bf16_f32 v56, v50, v51
	v_cvt_pk_bf16_f32 v57, v52, v53
	ds_write_b128 v146, v[54:57]
	ds_read_b128 v[62:65], v148
	v_cvt_f32_f16_sdwa v140, v145 dst_sel:DWORD dst_unused:UNUSED_PAD src0_sel:WORD_1
	v_pk_mul_f32 v[38:39], v[46:47], v[38:39]
	v_pk_mul_f32 v[40:41], v[48:49], v[40:41]
	v_pk_mul_f32 v[34:35], v[42:43], v[34:35]
	v_pk_mul_f32 v[36:37], v[44:45], v[36:37]
	v_mul_f32_e32 v142, 0xbfb8aa3b, v140
	v_mul_f32_e32 v144, v140, v140
	v_pk_mul_f32 v[46:47], v[46:47], v[142:143] op_sel_hi:[1,0]
	v_pk_mul_f32 v[48:49], v[48:49], v[142:143] op_sel_hi:[1,0]
	v_pk_mul_f32 v[42:43], v[42:43], v[142:143] op_sel_hi:[1,0]
	v_pk_mul_f32 v[44:45], v[44:45], v[142:143] op_sel_hi:[1,0]
	v_exp_f32_e32 v46, v46
	v_exp_f32_e32 v47, v47
	v_exp_f32_e32 v48, v48
	v_exp_f32_e32 v49, v49
	v_exp_f32_e32 v42, v42
	v_exp_f32_e32 v43, v43
	v_exp_f32_e32 v44, v44
	v_exp_f32_e32 v45, v45
	v_pk_mul_f32 v[38:39], v[38:39], v[144:145] op_sel_hi:[1,0]
	v_pk_mul_f32 v[40:41], v[40:41], v[144:145] op_sel_hi:[1,0]
	v_pk_mul_f32 v[34:35], v[34:35], v[144:145] op_sel_hi:[1,0]
	v_pk_mul_f32 v[36:37], v[36:37], v[144:145] op_sel_hi:[1,0]
	v_pk_add_f32 v[46:47], v[46:47], v[156:157]
	v_pk_add_f32 v[48:49], v[48:49], v[156:157]
	v_pk_add_f32 v[42:43], v[42:43], v[156:157]
	v_pk_add_f32 v[44:45], v[44:45], v[156:157]
	v_rcp_f32_e32 v46, v46
	v_rcp_f32_e32 v47, v47
	v_rcp_f32_e32 v48, v48
	v_rcp_f32_e32 v49, v49
	v_rcp_f32_e32 v42, v42
	v_rcp_f32_e32 v43, v43
	v_rcp_f32_e32 v44, v44
	v_rcp_f32_e32 v45, v45
	s_waitcnt lgkmcnt(0)
; __device__ __forceinline__ unsigned cvt_pk_bf16(float lo, float hi) { f32x2_t v = {lo, hi}; bf16x2_t b = __builtin_convertvector(v, bf16x2_t); return __builtin_bit_cast(unsigned, b); }
; __device__ __forceinline__ float silu_mul(float a, float b) { return a * b * __builtin_amdgcn_rcpf(1.0f + __builtin_amdgcn_exp2f(a * -1.4426950408889634f)); }
; #define PG8_BAR __builtin_amdgcn_s_barrier()
;     __device__ __forceinline__ void operator()(const f32x4 (&acc)[2][2][4][2], const Unit& u, int wr, int wc, int fr, int fq, const float (&rr)[2][4]) const {
;         const int row0 = u.pm * BM + wr * 64 + fr, col0 = u.pn * 128 + wc * 32 + 8 * fq;
; #pragma unroll
;         for (int ai = 0; ai < 2; ++ai)
; #pragma unroll
;             for (int m = 0; m < 4; ++m) { const int row = row0 + ai * HALF + m * 16; const float r = rr[ai][m];
;                 const f32x4 g0 = acc[ai][0][m][0] * r, g1 = acc[ai][0][m][1] * r, u0 = acc[ai][1][m][0] * r, u1 = acc[ai][1][m][1] * r;
;                 u32x4 w; w.x = cvt_pk_bf16(silu_mul(g0[0], u0[0]), silu_mul(g0[1], u0[1])); w.y = cvt_pk_bf16(silu_mul(g0[2], u0[2]), silu_mul(g0[3], u0[3]));
;                 w.z = cvt_pk_bf16(silu_mul(g1[0], u1[0]), silu_mul(g1[1], u1[1])); w.w = cvt_pk_bf16(silu_mul(g1[2], u1[2]), silu_mul(g1[3], u1[3]));
;                 *(u32x4*)(O + (size_t)row * ldc + col0) = w; }
;     ...
;         if (!has_next) break;
; #pragma unroll
;         for (int a = 0; a < 2; ++a)
; #pragma unroll
;             for (int b = 0; b < 2; ++b)
; #pragma unroll
;                 for (int m = 0; m < 4; ++m)
; #pragma unroll
;                     for (int n = 0; n < 2; ++n) acc[a][b][m][n] = (f32x4){0.f, 0.f, 0.f, 0.f};
;         cur = nxt; cA = nA; cB = nB; ++ui;
;         if constexpr (ALIGN_EPI) { if (wr == 1) PG8_BAR; }
	global_store_dwordx4 v[158:159], v[62:65], off
	v_pk_mul_f32 v[38:39], v[38:39], v[46:47]
	v_pk_mul_f32 v[40:41], v[40:41], v[48:49]
	v_pk_mul_f32 v[34:35], v[34:35], v[42:43]
	v_pk_mul_f32 v[36:37], v[36:37], v[44:45]
	v_cvt_pk_bf16_f32 v38, v38, v39
	v_cvt_pk_bf16_f32 v39, v40, v41
	v_cvt_pk_bf16_f32 v40, v34, v35
	v_cvt_pk_bf16_f32 v41, v36, v37
	ds_write_b128 v146, v[38:41]
	ds_read_b128 v[46:49], v148
	v_cvt_f32_f16_sdwa v140, v147 dst_sel:DWORD dst_unused:UNUSED_PAD src0_sel:WORD_1
	v_pk_mul_f32 v[22:23], v[30:31], v[22:23]
	v_pk_mul_f32 v[24:25], v[32:33], v[24:25]
	v_pk_mul_f32 v[18:19], v[26:27], v[18:19]
	v_pk_mul_f32 v[20:21], v[28:29], v[20:21]
	v_mul_f32_e32 v142, 0xbfb8aa3b, v140
	v_mul_f32_e32 v144, v140, v140
	v_pk_mul_f32 v[30:31], v[30:31], v[142:143] op_sel_hi:[1,0]
	v_pk_mul_f32 v[32:33], v[32:33], v[142:143] op_sel_hi:[1,0]
	v_pk_mul_f32 v[26:27], v[26:27], v[142:143] op_sel_hi:[1,0]
	v_pk_mul_f32 v[28:29], v[28:29], v[142:143] op_sel_hi:[1,0]
	v_exp_f32_e32 v30, v30
	v_exp_f32_e32 v31, v31
	v_exp_f32_e32 v32, v32
	v_exp_f32_e32 v33, v33
	v_exp_f32_e32 v26, v26
	v_exp_f32_e32 v27, v27
	v_exp_f32_e32 v28, v28
	v_exp_f32_e32 v29, v29
	v_pk_mul_f32 v[22:23], v[22:23], v[144:145] op_sel_hi:[1,0]
	v_pk_mul_f32 v[24:25], v[24:25], v[144:145] op_sel_hi:[1,0]
	v_pk_mul_f32 v[18:19], v[18:19], v[144:145] op_sel_hi:[1,0]
	v_pk_mul_f32 v[20:21], v[20:21], v[144:145] op_sel_hi:[1,0]
	v_pk_add_f32 v[30:31], v[30:31], v[156:157]
	v_pk_add_f32 v[32:33], v[32:33], v[156:157]
	v_pk_add_f32 v[26:27], v[26:27], v[156:157]
	v_pk_add_f32 v[28:29], v[28:29], v[156:157]
	v_rcp_f32_e32 v30, v30
	v_rcp_f32_e32 v31, v31
	v_rcp_f32_e32 v32, v32
	v_rcp_f32_e32 v33, v33
	v_rcp_f32_e32 v26, v26
	v_rcp_f32_e32 v27, v27
	v_rcp_f32_e32 v28, v28
	v_rcp_f32_e32 v29, v29
	s_mov_b64 s[6:7], 0x16000
	v_lshl_add_u64 v[158:159], v[158:159], 0, s[6:7]
	s_waitcnt lgkmcnt(0)
	global_store_dwordx4 v[158:159], v[46:49], off
	v_pk_mul_f32 v[22:23], v[22:23], v[30:31]
	v_pk_mul_f32 v[24:25], v[24:25], v[32:33]
	v_pk_mul_f32 v[18:19], v[18:19], v[26:27]
	v_pk_mul_f32 v[20:21], v[20:21], v[28:29]
	v_cvt_pk_bf16_f32 v22, v22, v23
	v_cvt_pk_bf16_f32 v23, v24, v25
	v_cvt_pk_bf16_f32 v24, v18, v19
	v_cvt_pk_bf16_f32 v25, v20, v21
	ds_write_b128 v146, v[22:25]
	ds_read_b128 v[30:33], v148
	v_cvt_f32_f16_sdwa v140, v149 dst_sel:DWORD dst_unused:UNUSED_PAD src0_sel:WORD_1
	v_pk_mul_f32 v[6:7], v[14:15], v[6:7]
	v_pk_mul_f32 v[8:9], v[16:17], v[8:9]
	v_pk_mul_f32 v[2:3], v[10:11], v[2:3]
	v_pk_mul_f32 v[4:5], v[12:13], v[4:5]
	v_mul_f32_e32 v142, 0xbfb8aa3b, v140
	v_mul_f32_e32 v144, v140, v140
	v_pk_mul_f32 v[14:15], v[14:15], v[142:143] op_sel_hi:[1,0]
	v_pk_mul_f32 v[16:17], v[16:17], v[142:143] op_sel_hi:[1,0]
	v_pk_mul_f32 v[10:11], v[10:11], v[142:143] op_sel_hi:[1,0]
	v_pk_mul_f32 v[12:13], v[12:13], v[142:143] op_sel_hi:[1,0]
	v_exp_f32_e32 v14, v14
	v_exp_f32_e32 v15, v15
	v_exp_f32_e32 v16, v16
	v_exp_f32_e32 v17, v17
	v_exp_f32_e32 v10, v10
	v_exp_f32_e32 v11, v11
	v_exp_f32_e32 v12, v12
	v_exp_f32_e32 v13, v13
	v_pk_mul_f32 v[6:7], v[6:7], v[144:145] op_sel_hi:[1,0]
	v_pk_mul_f32 v[8:9], v[8:9], v[144:145] op_sel_hi:[1,0]
	v_pk_mul_f32 v[2:3], v[2:3], v[144:145] op_sel_hi:[1,0]
	v_pk_mul_f32 v[4:5], v[4:5], v[144:145] op_sel_hi:[1,0]
	v_pk_add_f32 v[14:15], v[14:15], v[156:157]
	v_pk_add_f32 v[16:17], v[16:17], v[156:157]
	v_pk_add_f32 v[10:11], v[10:11], v[156:157]
	v_pk_add_f32 v[12:13], v[12:13], v[156:157]
	v_rcp_f32_e32 v14, v14
	v_rcp_f32_e32 v15, v15
	v_rcp_f32_e32 v16, v16
	v_rcp_f32_e32 v17, v17
	v_rcp_f32_e32 v10, v10
	v_rcp_f32_e32 v11, v11
	v_rcp_f32_e32 v12, v12
	v_rcp_f32_e32 v13, v13
	s_mov_b64 s[6:7], 0x16000
	v_lshl_add_u64 v[158:159], v[158:159], 0, s[6:7]
	s_waitcnt lgkmcnt(0)
	global_store_dwordx4 v[158:159], v[30:33], off
	v_pk_mul_f32 v[6:7], v[6:7], v[14:15]
	v_pk_mul_f32 v[8:9], v[8:9], v[16:17]
	v_pk_mul_f32 v[2:3], v[2:3], v[10:11]
	v_pk_mul_f32 v[4:5], v[4:5], v[12:13]
	v_cvt_pk_bf16_f32 v6, v6, v7
	v_cvt_pk_bf16_f32 v7, v8, v9
	v_cvt_pk_bf16_f32 v8, v2, v3
	v_cvt_pk_bf16_f32 v9, v4, v5
	ds_write_b128 v146, v[6:9]
	ds_read_b128 v[14:17], v148
	s_mov_b64 s[6:7], 0x16000
	v_lshl_add_u64 v[158:159], v[158:159], 0, s[6:7]
	s_waitcnt lgkmcnt(0)
	global_store_dwordx4 v[158:159], v[14:17], off
.Lepi_end:
	s_and_b64 vcc, exec, s[38:39]
	s_mov_b64 s[6:7], -1
	s_cbranch_vccnz .LBB0_604
	s_andn2_b64 vcc, exec, s[72:73]
	s_cbranch_vccnz .LBB0_603
	s_barrier
	s_branch .LBB0_603
; #define PG8_STAGE(bufoff, gbase, voff) do { _Pragma("unroll") for (int _i = 0; _i < 2; ++_i) \
;         __builtin_amdgcn_global_load_lds((const unsigned*)((const char*)(gbase) + (voff)[_i]), (PG8_LAS unsigned*)(lds + (bufoff) + ldsw + _i * 8192), 16, 0, 0); } while (0)
; #define PG8_LDA(dst, b, h) do { _Pragma("unroll") for (int m = 0; m < 4; ++m) _Pragma("unroll") for (int k = 0; k < 2; ++k) dst[m][k] = *(const PG8_LAS bf16x8*)(lds + PG8_SA(b, h) + aoff + m * 2048 + k * 1024); } while (0)
; #define PG8_LDB(dst, b, h) do { _Pragma("unroll") for (int n = 0; n < 2; ++n) _Pragma("unroll") for (int k = 0; k < 2; ++k) dst[n][k] = *(const PG8_LAS bf16x8*)(lds + PG8_SB(b, h) + boff + n * 2048 + k * 1024); } while (0)
; #define PG8_MMA(ai, bj, At, Bt) do { __builtin_amdgcn_s_setprio(1); _Pragma("unroll") for (int m = 0; m < 4; ++m) _Pragma("unroll") for (int n = 0; n < 2; ++n) _Pragma("unroll") for (int k = 0; k < 2; ++k) \
;         acc[ai][bj][m][n] = __builtin_amdgcn_mfma_f32_16x16x32_bf16(Bt[n][k], At[m][k], acc[ai][bj][m][n], 0, 0, 0); __builtin_amdgcn_s_setprio(0); } while (0)
; #define PG8_WAIT_V(n) asm volatile("s_waitcnt vmcnt(" #n ")" ::: "memory")
; #define PG8_WAIT_L(n) asm volatile("s_waitcnt lgkmcnt(" #n ")" ::: "memory")
; #define PG8_BAR __builtin_amdgcn_s_barrier()
; #define PG8_SCHED __builtin_amdgcn_sched_barrier(0)
;     ...
;         for (int t = 0; t < nt; t += 2) {
;             const bool last = (t == nt - 2);
;             const char* a1 = cA + (size_t)(t + 1) * kstep;
;             const char* a2 = last ? nA : cA + (size_t)(t + 2) * kstep; const char* b2 = last ? nB : cB + (size_t)(t + 2) * kstep;
;             const char* a3 = a2 + kstep; const char* b3 = b2 + kstep;
;             if (last && has_next) S.a_ready(nxt);
;             if constexpr (SP2) {
;             PG8_LDB(B0, 0, 0); PG8_LDB(B1, 0, 1); PG8_SCHED; PG8_LDA(At, 0, 0); PG8_STAGE(PG8_SA(1, 1), a1 + hstepA, voffA);
;             PG8_WAIT_V(8); PG8_WAIT_L(0); PG8_BAR; PG8_MMA(0, 0, At, B0); PG8_MMA(0, 1, At, B1); PG8_BAR; PG8_SCHED;
;             PG8_LDA(At, 0, 1); PG8_STAGE(PG8_SB(0, 0), b2, voffB); PG8_STAGE(PG8_SB(0, 1), b2 + hstepB, voffB); PG8_STAGE(PG8_SA(0, 0), a2, voffA);
;             PG8_WAIT_V(8); PG8_WAIT_L(0); PG8_BAR; PG8_MMA(1, 0, At, B0); PG8_MMA(1, 1, At, B1); PG8_BAR; PG8_SCHED;
.Lhalf_entry:
	s_add_u32 s24, s8, 0x100
	s_addc_u32 s25, s9, 0
	s_add_u32 s6, s10, 0x80
	s_addc_u32 s7, s11, 0
	s_mov_b32 s8, 0
	s_add_i32 s10, s8, 2
	s_add_u32 s11, s6, 0x80
	s_addc_u32 s9, s7, 0
	s_add_i32 s27, 0, 0x10000
	s_cmp_eq_u32 s18, s8
	s_cselect_b32 s9, s41, s9
	s_cselect_b32 s8, s40, s11
	v_add_u32_e32 v140, s27, v151
	s_cselect_b32 s35, s91, s25
	s_cselect_b32 s34, s90, s24
	s_add_i32 s11, 0, 0x14000
	ds_read_b128 v[156:159], v140
	ds_read_b128 v[160:163], v140 offset:1024
	ds_read_b128 v[172:175], v140 offset:2048
	ds_read_b128 v[176:179], v140 offset:3072
	v_add_u32_e32 v140, s11, v151
	ds_read_b128 v[180:183], v140
	ds_read_b128 v[184:187], v140 offset:1024
	ds_read_b128 v[188:191], v140 offset:2048
	ds_read_b128 v[192:195], v140 offset:3072
	v_lshl_add_u64 v[164:165], s[6:7], 0, v[138:139]
	s_add_i32 m0, s3, 0xc000
	ds_read_b128 v[196:199], v154
	ds_read_b128 v[200:203], v154 offset:1024
	ds_read_b128 v[204:207], v154 offset:2048
	ds_read_b128 v[208:211], v154 offset:3072
	ds_read_b128 v[212:215], v154 offset:4096
	ds_read_b128 v[216:219], v154 offset:5120
	ds_read_b128 v[220:223], v154 offset:6144
	ds_read_b128 v[224:227], v154 offset:7168
	global_load_lds_dwordx4 v[164:165], off
	v_lshl_add_u64 v[164:165], s[6:7], 0, v[136:137]
	s_add_i32 m0, s3, 0xe000
	s_nop 0
	global_load_lds_dwordx4 v[164:165], off
	s_waitcnt vmcnt(8)
	s_waitcnt lgkmcnt(0)
	s_barrier
	s_waitcnt lgkmcnt(0)
	s_bitcmp1_b32 s101, 1
	s_cbranch_scc1 .Lmfskip0
	v_mfma_f32_16x16x32_bf16 v[126:129], v[156:159], v[196:199], 0
	v_mfma_f32_16x16x32_bf16 v[122:125], v[172:175], v[196:199], 0
	v_mfma_f32_16x16x32_bf16 v[110:113], v[156:159], v[204:207], 0
	v_mfma_f32_16x16x32_bf16 v[106:109], v[172:175], v[204:207], 0
	v_mfma_f32_16x16x32_bf16 v[94:97], v[156:159], v[212:215], 0
	v_mfma_f32_16x16x32_bf16 v[90:93], v[172:175], v[212:215], 0
	v_mfma_f32_16x16x32_bf16 v[78:81], v[156:159], v[220:223], 0
	v_mfma_f32_16x16x32_bf16 v[74:77], v[172:175], v[220:223], 0
	v_mfma_f32_16x16x32_bf16 v[126:129], v[160:163], v[200:203], v[126:129]
	v_mfma_f32_16x16x32_bf16 v[122:125], v[176:179], v[200:203], v[122:125]
	v_mfma_f32_16x16x32_bf16 v[110:113], v[160:163], v[208:211], v[110:113]
	v_mfma_f32_16x16x32_bf16 v[106:109], v[176:179], v[208:211], v[106:109]
	v_mfma_f32_16x16x32_bf16 v[94:97], v[160:163], v[216:219], v[94:97]
	v_mfma_f32_16x16x32_bf16 v[90:93], v[176:179], v[216:219], v[90:93]
	v_mfma_f32_16x16x32_bf16 v[78:81], v[160:163], v[224:227], v[78:81]
	v_mfma_f32_16x16x32_bf16 v[74:77], v[176:179], v[224:227], v[74:77]
	v_mfma_f32_16x16x32_bf16 v[118:121], v[180:183], v[196:199], 0
	v_mfma_f32_16x16x32_bf16 v[114:117], v[188:191], v[196:199], 0
	v_mfma_f32_16x16x32_bf16 v[102:105], v[180:183], v[204:207], 0
	v_mfma_f32_16x16x32_bf16 v[98:101], v[188:191], v[204:207], 0
	v_mfma_f32_16x16x32_bf16 v[86:89], v[180:183], v[212:215], 0
	v_mfma_f32_16x16x32_bf16 v[82:85], v[188:191], v[212:215], 0
	v_mfma_f32_16x16x32_bf16 v[70:73], v[180:183], v[220:223], 0
	v_mfma_f32_16x16x32_bf16 v[66:69], v[188:191], v[220:223], 0
	v_mfma_f32_16x16x32_bf16 v[118:121], v[184:187], v[200:203], v[118:121]
	v_mfma_f32_16x16x32_bf16 v[114:117], v[192:195], v[200:203], v[114:117]
	v_mfma_f32_16x16x32_bf16 v[102:105], v[184:187], v[208:211], v[102:105]
	v_mfma_f32_16x16x32_bf16 v[98:101], v[192:195], v[208:211], v[98:101]
	v_mfma_f32_16x16x32_bf16 v[86:89], v[184:187], v[216:219], v[86:89]
	v_mfma_f32_16x16x32_bf16 v[82:85], v[192:195], v[216:219], v[82:85]
	v_mfma_f32_16x16x32_bf16 v[70:73], v[184:187], v[224:227], v[70:73]
	v_mfma_f32_16x16x32_bf16 v[66:69], v[192:195], v[224:227], v[66:69]
.Lmfskip0:
	s_barrier
	s_add_i32 s27, s27, s0
	v_lshl_add_u64 v[164:165], s[34:35], 0, v[166:167]
	s_mov_b32 m0, s27
	ds_read_b128 v[196:199], v154 offset:16384
	ds_read_b128 v[200:203], v154 offset:17408
	ds_read_b128 v[204:207], v154 offset:18432
	ds_read_b128 v[208:211], v154 offset:19456
	ds_read_b128 v[212:215], v154 offset:20480
	ds_read_b128 v[216:219], v154 offset:21504
	ds_read_b128 v[220:223], v154 offset:22528
	ds_read_b128 v[224:227], v154 offset:23552
	global_load_lds_dwordx4 v[164:165], off
	s_add_i32 m0, s27, 0x2000
	v_lshl_add_u64 v[168:169], s[34:35], 0, v[130:131]
	s_add_u32 s34, s34, s58
	s_addc_u32 s35, s35, s59
	s_add_i32 s11, s11, s0
	global_load_lds_dwordx4 v[168:169], off
	v_lshl_add_u64 v[170:171], s[34:35], 0, v[166:167]
	s_mov_b32 m0, s11
	v_lshl_add_u64 v[228:229], s[34:35], 0, v[130:131]
	global_load_lds_dwordx4 v[170:171], off
	s_add_i32 m0, s11, 0x2000
	v_lshl_add_u64 v[230:231], s[8:9], 0, v[134:135]
	global_load_lds_dwordx4 v[228:229], off
	s_mov_b32 m0, s3
	v_lshl_add_u64 v[232:233], s[8:9], 0, v[132:133]
	global_load_lds_dwordx4 v[230:231], off
	s_mov_b32 m0, s12
	s_nop 0
	global_load_lds_dwordx4 v[232:233], off
	s_waitcnt vmcnt(8)
	s_waitcnt lgkmcnt(0)
	s_barrier
	s_waitcnt lgkmcnt(0)
	s_bitcmp1_b32 s101, 0
	s_cbranch_scc1 .Lmfskip1
	v_mfma_f32_16x16x32_bf16 v[62:65], v[156:159], v[196:199], 0
	v_mfma_f32_16x16x32_bf16 v[58:61], v[172:175], v[196:199], 0
	v_mfma_f32_16x16x32_bf16 v[46:49], v[156:159], v[204:207], 0
	v_mfma_f32_16x16x32_bf16 v[42:45], v[172:175], v[204:207], 0
	v_mfma_f32_16x16x32_bf16 v[30:33], v[156:159], v[212:215], 0
	v_mfma_f32_16x16x32_bf16 v[26:29], v[172:175], v[212:215], 0
	v_mfma_f32_16x16x32_bf16 v[14:17], v[156:159], v[220:223], 0
	v_mfma_f32_16x16x32_bf16 v[10:13], v[172:175], v[220:223], 0
	v_mfma_f32_16x16x32_bf16 v[62:65], v[160:163], v[200:203], v[62:65]
	v_mfma_f32_16x16x32_bf16 v[58:61], v[176:179], v[200:203], v[58:61]
	v_mfma_f32_16x16x32_bf16 v[46:49], v[160:163], v[208:211], v[46:49]
	v_mfma_f32_16x16x32_bf16 v[42:45], v[176:179], v[208:211], v[42:45]
	v_mfma_f32_16x16x32_bf16 v[30:33], v[160:163], v[216:219], v[30:33]
	v_mfma_f32_16x16x32_bf16 v[26:29], v[176:179], v[216:219], v[26:29]
	v_mfma_f32_16x16x32_bf16 v[14:17], v[160:163], v[224:227], v[14:17]
	v_mfma_f32_16x16x32_bf16 v[10:13], v[176:179], v[224:227], v[10:13]
	v_mfma_f32_16x16x32_bf16 v[54:57], v[180:183], v[196:199], 0
	v_mfma_f32_16x16x32_bf16 v[50:53], v[188:191], v[196:199], 0
	v_mfma_f32_16x16x32_bf16 v[38:41], v[180:183], v[204:207], 0
	v_mfma_f32_16x16x32_bf16 v[34:37], v[188:191], v[204:207], 0
	v_mfma_f32_16x16x32_bf16 v[22:25], v[180:183], v[212:215], 0
	v_mfma_f32_16x16x32_bf16 v[18:21], v[188:191], v[212:215], 0
	v_mfma_f32_16x16x32_bf16 v[6:9], v[180:183], v[220:223], 0
	v_mfma_f32_16x16x32_bf16 v[2:5], v[188:191], v[220:223], 0
	v_mfma_f32_16x16x32_bf16 v[54:57], v[184:187], v[200:203], v[54:57]
	v_mfma_f32_16x16x32_bf16 v[50:53], v[192:195], v[200:203], v[50:53]
	v_mfma_f32_16x16x32_bf16 v[38:41], v[184:187], v[208:211], v[38:41]
	v_mfma_f32_16x16x32_bf16 v[34:37], v[192:195], v[208:211], v[34:37]
	v_mfma_f32_16x16x32_bf16 v[22:25], v[184:187], v[216:219], v[22:25]
	v_mfma_f32_16x16x32_bf16 v[18:21], v[192:195], v[216:219], v[18:21]
	v_mfma_f32_16x16x32_bf16 v[6:9], v[184:187], v[224:227], v[6:9]
	v_mfma_f32_16x16x32_bf16 v[2:5], v[192:195], v[224:227], v[2:5]
; #define PG8_STAGE(bufoff, gbase, voff) do { _Pragma("unroll") for (int _i = 0; _i < 2; ++_i) \
;         __builtin_amdgcn_global_load_lds((const unsigned*)((const char*)(gbase) + (voff)[_i]), (PG8_LAS unsigned*)(lds + (bufoff) + ldsw + _i * 8192), 16, 0, 0); } while (0)
; #define PG8_LDA(dst, b, h) do { _Pragma("unroll") for (int m = 0; m < 4; ++m) _Pragma("unroll") for (int k = 0; k < 2; ++k) dst[m][k] = *(const PG8_LAS bf16x8*)(lds + PG8_SA(b, h) + aoff + m * 2048 + k * 1024); } while (0)
; #define PG8_LDB(dst, b, h) do { _Pragma("unroll") for (int n = 0; n < 2; ++n) _Pragma("unroll") for (int k = 0; k < 2; ++k) dst[n][k] = *(const PG8_LAS bf16x8*)(lds + PG8_SB(b, h) + boff + n * 2048 + k * 1024); } while (0)
; #define PG8_MMA(ai, bj, At, Bt) do { __builtin_amdgcn_s_setprio(1); _Pragma("unroll") for (int m = 0; m < 4; ++m) _Pragma("unroll") for (int n = 0; n < 2; ++n) _Pragma("unroll") for (int k = 0; k < 2; ++k) \
;         acc[ai][bj][m][n] = __builtin_amdgcn_mfma_f32_16x16x32_bf16(Bt[n][k], At[m][k], acc[ai][bj][m][n], 0, 0, 0); __builtin_amdgcn_s_setprio(0); } while (0)
; #define PG8_WAIT_V(n) asm volatile("s_waitcnt vmcnt(" #n ")" ::: "memory")
; #define PG8_WAIT_L(n) asm volatile("s_waitcnt lgkmcnt(" #n ")" ::: "memory")
; #define PG8_BAR __builtin_amdgcn_s_barrier()
; #define PG8_SCHED __builtin_amdgcn_sched_barrier(0)
;     ...
;             PG8_LDB(B0, 1, 0); PG8_LDB(B1, 1, 1); PG8_SCHED; PG8_LDA(At, 1, 0); PG8_STAGE(PG8_SA(0, 1), a2 + hstepA, voffA);
;             PG8_WAIT_V(8); PG8_WAIT_L(0); PG8_BAR; PG8_MMA(0, 0, At, B0); PG8_MMA(0, 1, At, B1); PG8_BAR; PG8_SCHED;
;             PG8_LDA(At, 1, 1); PG8_STAGE(PG8_SB(1, 0), b3, voffB); PG8_STAGE(PG8_SB(1, 1), b3 + hstepB, voffB); PG8_STAGE(PG8_SA(1, 0), a3, voffA);
;             PG8_WAIT_V(8); PG8_WAIT_L(0); PG8_BAR; PG8_MMA(1, 0, At, B0); PG8_MMA(1, 1, At, B1); PG8_BAR; PG8_SCHED;
.Lmfskip1:
	s_barrier
	s_add_i32 s11, 0, 0x18000
	v_add_u32_e32 v140, s11, v151
	s_add_i32 s27, 0, 0x1c000
	ds_read_b128 v[156:159], v140
	ds_read_b128 v[160:163], v140 offset:1024
	ds_read_b128 v[172:175], v140 offset:2048
	ds_read_b128 v[176:179], v140 offset:3072
	v_add_u32_e32 v140, s27, v151
	ds_read_b128 v[180:183], v140
	ds_read_b128 v[184:187], v140 offset:1024
	ds_read_b128 v[188:191], v140 offset:2048
	ds_read_b128 v[192:195], v140 offset:3072
	s_add_u32 s8, s8, s58
	s_addc_u32 s9, s9, s59
	s_mov_b32 m0, s13
	v_lshl_add_u64 v[234:235], s[8:9], 0, v[134:135]
	ds_read_b128 v[196:199], v154 offset:32768
	ds_read_b128 v[200:203], v154 offset:33792
	ds_read_b128 v[204:207], v154 offset:34816
	ds_read_b128 v[208:211], v154 offset:35840
	ds_read_b128 v[212:215], v154 offset:36864
	ds_read_b128 v[216:219], v154 offset:37888
	ds_read_b128 v[220:223], v154 offset:38912
	ds_read_b128 v[224:227], v154 offset:39936
	global_load_lds_dwordx4 v[234:235], off
	v_lshl_add_u64 v[234:235], s[8:9], 0, v[132:133]
	s_mov_b32 m0, s14
	s_nop 0
	global_load_lds_dwordx4 v[234:235], off
	s_waitcnt vmcnt(8)
	s_waitcnt lgkmcnt(0)
	s_barrier
	s_waitcnt lgkmcnt(0)
	s_bitcmp1_b32 s101, 1
	s_cbranch_scc1 .Lmfskip2
	v_mfma_f32_16x16x32_bf16 v[126:129], v[156:159], v[196:199], v[126:129]
	v_mfma_f32_16x16x32_bf16 v[122:125], v[172:175], v[196:199], v[122:125]
	v_mfma_f32_16x16x32_bf16 v[110:113], v[156:159], v[204:207], v[110:113]
	v_mfma_f32_16x16x32_bf16 v[106:109], v[172:175], v[204:207], v[106:109]
	v_mfma_f32_16x16x32_bf16 v[94:97], v[156:159], v[212:215], v[94:97]
	v_mfma_f32_16x16x32_bf16 v[90:93], v[172:175], v[212:215], v[90:93]
	v_mfma_f32_16x16x32_bf16 v[78:81], v[156:159], v[220:223], v[78:81]
	v_mfma_f32_16x16x32_bf16 v[74:77], v[172:175], v[220:223], v[74:77]
	v_mfma_f32_16x16x32_bf16 v[126:129], v[160:163], v[200:203], v[126:129]
	v_mfma_f32_16x16x32_bf16 v[122:125], v[176:179], v[200:203], v[122:125]
	v_mfma_f32_16x16x32_bf16 v[110:113], v[160:163], v[208:211], v[110:113]
	v_mfma_f32_16x16x32_bf16 v[106:109], v[176:179], v[208:211], v[106:109]
	v_mfma_f32_16x16x32_bf16 v[94:97], v[160:163], v[216:219], v[94:97]
	v_mfma_f32_16x16x32_bf16 v[90:93], v[176:179], v[216:219], v[90:93]
	v_mfma_f32_16x16x32_bf16 v[78:81], v[160:163], v[224:227], v[78:81]
	v_mfma_f32_16x16x32_bf16 v[74:77], v[176:179], v[224:227], v[74:77]
	v_mfma_f32_16x16x32_bf16 v[118:121], v[180:183], v[196:199], v[118:121]
	v_mfma_f32_16x16x32_bf16 v[114:117], v[188:191], v[196:199], v[114:117]
	v_mfma_f32_16x16x32_bf16 v[102:105], v[180:183], v[204:207], v[102:105]
	v_mfma_f32_16x16x32_bf16 v[98:101], v[188:191], v[204:207], v[98:101]
	v_mfma_f32_16x16x32_bf16 v[86:89], v[180:183], v[212:215], v[86:89]
	v_mfma_f32_16x16x32_bf16 v[82:85], v[188:191], v[212:215], v[82:85]
	v_mfma_f32_16x16x32_bf16 v[70:73], v[180:183], v[220:223], v[70:73]
	v_mfma_f32_16x16x32_bf16 v[66:69], v[188:191], v[220:223], v[66:69]
	v_mfma_f32_16x16x32_bf16 v[118:121], v[184:187], v[200:203], v[118:121]
	v_mfma_f32_16x16x32_bf16 v[114:117], v[192:195], v[200:203], v[114:117]
	v_mfma_f32_16x16x32_bf16 v[102:105], v[184:187], v[208:211], v[102:105]
	v_mfma_f32_16x16x32_bf16 v[98:101], v[192:195], v[208:211], v[98:101]
	v_mfma_f32_16x16x32_bf16 v[86:89], v[184:187], v[216:219], v[86:89]
	v_mfma_f32_16x16x32_bf16 v[82:85], v[192:195], v[216:219], v[82:85]
	v_mfma_f32_16x16x32_bf16 v[70:73], v[184:187], v[224:227], v[70:73]
	v_mfma_f32_16x16x32_bf16 v[66:69], v[192:195], v[224:227], v[66:69]
.Lmfskip2:
	s_barrier
	s_add_i32 s8, s11, s0
	v_lshl_add_u64 v[164:165], v[164:165], 0, s[62:63]
	s_mov_b32 m0, s8
	ds_read_b128 v[196:199], v154 offset:49152
	ds_read_b128 v[200:203], v154 offset:50176
	ds_read_b128 v[204:207], v154 offset:51200
	ds_read_b128 v[208:211], v154 offset:52224
	ds_read_b128 v[212:215], v154 offset:53248
	ds_read_b128 v[216:219], v154 offset:54272
	ds_read_b128 v[220:223], v154 offset:55296
	ds_read_b128 v[224:227], v154 offset:56320
	global_load_lds_dwordx4 v[164:165], off
	v_lshl_add_u64 v[164:165], v[168:169], 0, s[62:63]
	s_add_i32 m0, s8, 0x2000
	s_add_i32 s8, s27, s0
	global_load_lds_dwordx4 v[164:165], off
	v_lshl_add_u64 v[164:165], v[170:171], 0, s[62:63]
	s_mov_b32 m0, s8
	s_nop 0
	global_load_lds_dwordx4 v[164:165], off
	v_lshl_add_u64 v[164:165], v[228:229], 0, s[62:63]
	s_add_i32 m0, s8, 0x2000
	s_nop 0
	global_load_lds_dwordx4 v[164:165], off
	v_lshl_add_u64 v[164:165], v[230:231], 0, s[62:63]
	s_mov_b32 m0, s16
	s_nop 0
	global_load_lds_dwordx4 v[164:165], off
	v_lshl_add_u64 v[164:165], v[232:233], 0, s[62:63]
	s_mov_b32 m0, s17
	s_nop 0
	global_load_lds_dwordx4 v[164:165], off
	s_waitcnt vmcnt(8)
	s_waitcnt lgkmcnt(0)
	s_barrier
	s_waitcnt lgkmcnt(0)
	s_bitcmp1_b32 s101, 0
	s_cbranch_scc1 .Lmfskip3
	v_mfma_f32_16x16x32_bf16 v[62:65], v[156:159], v[196:199], v[62:65]
	v_mfma_f32_16x16x32_bf16 v[58:61], v[172:175], v[196:199], v[58:61]
	v_mfma_f32_16x16x32_bf16 v[46:49], v[156:159], v[204:207], v[46:49]
	v_mfma_f32_16x16x32_bf16 v[42:45], v[172:175], v[204:207], v[42:45]
	v_mfma_f32_16x16x32_bf16 v[30:33], v[156:159], v[212:215], v[30:33]
	v_mfma_f32_16x16x32_bf16 v[26:29], v[172:175], v[212:215], v[26:29]
	v_mfma_f32_16x16x32_bf16 v[14:17], v[156:159], v[220:223], v[14:17]
	v_mfma_f32_16x16x32_bf16 v[10:13], v[172:175], v[220:223], v[10:13]
	v_mfma_f32_16x16x32_bf16 v[62:65], v[160:163], v[200:203], v[62:65]
	v_mfma_f32_16x16x32_bf16 v[58:61], v[176:179], v[200:203], v[58:61]
	v_mfma_f32_16x16x32_bf16 v[46:49], v[160:163], v[208:211], v[46:49]
	v_mfma_f32_16x16x32_bf16 v[42:45], v[176:179], v[208:211], v[42:45]
	v_mfma_f32_16x16x32_bf16 v[30:33], v[160:163], v[216:219], v[30:33]
	v_mfma_f32_16x16x32_bf16 v[26:29], v[176:179], v[216:219], v[26:29]
	v_mfma_f32_16x16x32_bf16 v[14:17], v[160:163], v[224:227], v[14:17]
	v_mfma_f32_16x16x32_bf16 v[10:13], v[176:179], v[224:227], v[10:13]
	v_mfma_f32_16x16x32_bf16 v[54:57], v[180:183], v[196:199], v[54:57]
	v_mfma_f32_16x16x32_bf16 v[50:53], v[188:191], v[196:199], v[50:53]
	v_mfma_f32_16x16x32_bf16 v[38:41], v[180:183], v[204:207], v[38:41]
	v_mfma_f32_16x16x32_bf16 v[34:37], v[188:191], v[204:207], v[34:37]
	v_mfma_f32_16x16x32_bf16 v[22:25], v[180:183], v[212:215], v[22:25]
	v_mfma_f32_16x16x32_bf16 v[18:21], v[188:191], v[212:215], v[18:21]
	v_mfma_f32_16x16x32_bf16 v[6:9], v[180:183], v[220:223], v[6:9]
	v_mfma_f32_16x16x32_bf16 v[2:5], v[188:191], v[220:223], v[2:5]
	v_mfma_f32_16x16x32_bf16 v[54:57], v[184:187], v[200:203], v[54:57]
	v_mfma_f32_16x16x32_bf16 v[50:53], v[192:195], v[200:203], v[50:53]
	v_mfma_f32_16x16x32_bf16 v[38:41], v[184:187], v[208:211], v[38:41]
	v_mfma_f32_16x16x32_bf16 v[34:37], v[192:195], v[208:211], v[34:37]
	v_mfma_f32_16x16x32_bf16 v[22:25], v[184:187], v[216:219], v[22:25]
	v_mfma_f32_16x16x32_bf16 v[18:21], v[192:195], v[216:219], v[18:21]
	v_mfma_f32_16x16x32_bf16 v[6:9], v[184:187], v[224:227], v[6:9]
	v_mfma_f32_16x16x32_bf16 v[2:5], v[192:195], v[224:227], v[2:5]
; #define PG8_STAGE(bufoff, gbase, voff) do { _Pragma("unroll") for (int _i = 0; _i < 2; ++_i) \
;         __builtin_amdgcn_global_load_lds((const unsigned*)((const char*)(gbase) + (voff)[_i]), (PG8_LAS unsigned*)(lds + (bufoff) + ldsw + _i * 8192), 16, 0, 0); } while (0)
; #define PG8_LDA(dst, b, h) do { _Pragma("unroll") for (int m = 0; m < 4; ++m) _Pragma("unroll") for (int k = 0; k < 2; ++k) dst[m][k] = *(const PG8_LAS bf16x8*)(lds + PG8_SA(b, h) + aoff + m * 2048 + k * 1024); } while (0)
; #define PG8_LDB(dst, b, h) do { _Pragma("unroll") for (int n = 0; n < 2; ++n) _Pragma("unroll") for (int k = 0; k < 2; ++k) dst[n][k] = *(const PG8_LAS bf16x8*)(lds + PG8_SB(b, h) + boff + n * 2048 + k * 1024); } while (0)
; #define PG8_MMA(ai, bj, At, Bt) do { __builtin_amdgcn_s_setprio(1); _Pragma("unroll") for (int m = 0; m < 4; ++m) _Pragma("unroll") for (int n = 0; n < 2; ++n) _Pragma("unroll") for (int k = 0; k < 2; ++k) \
;         acc[ai][bj][m][n] = __builtin_amdgcn_mfma_f32_16x16x32_bf16(Bt[n][k], At[m][k], acc[ai][bj][m][n], 0, 0, 0); __builtin_amdgcn_s_setprio(0); } while (0)
; #define PG8_WAIT_V(n) asm volatile("s_waitcnt vmcnt(" #n ")" ::: "memory")
; #define PG8_WAIT_L(n) asm volatile("s_waitcnt lgkmcnt(" #n ")" ::: "memory")
; #define PG8_BAR __builtin_amdgcn_s_barrier()
; #define PG8_SCHED __builtin_amdgcn_sched_barrier(0)
;     ...
;         for (int t = 0; t < nt; t += 2) {
;             const bool last = (t == nt - 2);
;             const char* a1 = cA + (size_t)(t + 1) * kstep;
;             const char* a2 = last ? nA : cA + (size_t)(t + 2) * kstep; const char* b2 = last ? nB : cB + (size_t)(t + 2) * kstep;
;             const char* a3 = a2 + kstep; const char* b3 = b2 + kstep;
;             if (last && has_next) S.a_ready(nxt);
;             if constexpr (SP2) {
;             PG8_LDB(B0, 0, 0); PG8_LDB(B1, 0, 1); PG8_SCHED; PG8_LDA(At, 0, 0); PG8_STAGE(PG8_SA(1, 1), a1 + hstepA, voffA);
;             PG8_WAIT_V(8); PG8_WAIT_L(0); PG8_BAR; PG8_MMA(0, 0, At, B0); PG8_MMA(0, 1, At, B1); PG8_BAR; PG8_SCHED;
;             PG8_LDA(At, 0, 1); PG8_STAGE(PG8_SB(0, 0), b2, voffB); PG8_STAGE(PG8_SB(0, 1), b2 + hstepB, voffB); PG8_STAGE(PG8_SA(0, 0), a2, voffA);
;             PG8_WAIT_V(8); PG8_WAIT_L(0); PG8_BAR; PG8_MMA(1, 0, At, B0); PG8_MMA(1, 1, At, B1); PG8_BAR; PG8_SCHED;
.Lmfskip3:
	s_barrier
	s_add_u32 s24, s24, 0x100
	s_addc_u32 s25, s25, 0
	s_add_u32 s6, s6, 0x100
	s_addc_u32 s7, s7, 0
	s_cmp_ge_i32 s10, s15
	s_mov_b32 s8, s10
	s_cbranch_scc1 .LBB0_614
.Lhalf_613:
	s_add_i32 s10, s8, 2
	s_add_u32 s11, s6, 0x80
	s_addc_u32 s9, s7, 0
	s_add_i32 s27, 0, 0x10000
	s_cmp_eq_u32 s18, s8
	s_cselect_b32 s9, s41, s9
	s_cselect_b32 s8, s40, s11
	v_add_u32_e32 v140, s27, v151
	s_cselect_b32 s35, s91, s25
	s_cselect_b32 s34, s90, s24
	s_add_i32 s11, 0, 0x14000
	ds_read_b128 v[156:159], v140
	ds_read_b128 v[160:163], v140 offset:1024
	ds_read_b128 v[172:175], v140 offset:2048
	ds_read_b128 v[176:179], v140 offset:3072
	v_add_u32_e32 v140, s11, v151
	ds_read_b128 v[180:183], v140
	ds_read_b128 v[184:187], v140 offset:1024
	ds_read_b128 v[188:191], v140 offset:2048
	ds_read_b128 v[192:195], v140 offset:3072
	v_lshl_add_u64 v[164:165], s[6:7], 0, v[138:139]
	s_add_i32 m0, s3, 0xc000
	ds_read_b128 v[196:199], v154
	ds_read_b128 v[200:203], v154 offset:1024
	ds_read_b128 v[204:207], v154 offset:2048
	ds_read_b128 v[208:211], v154 offset:3072
	ds_read_b128 v[212:215], v154 offset:4096
	ds_read_b128 v[216:219], v154 offset:5120
	ds_read_b128 v[220:223], v154 offset:6144
	ds_read_b128 v[224:227], v154 offset:7168
	global_load_lds_dwordx4 v[164:165], off
	v_lshl_add_u64 v[164:165], s[6:7], 0, v[136:137]
	s_add_i32 m0, s3, 0xe000
	s_nop 0
	global_load_lds_dwordx4 v[164:165], off
	s_waitcnt vmcnt(8)
	s_waitcnt lgkmcnt(0)
	s_barrier
	s_waitcnt lgkmcnt(0)
	s_bitcmp1_b32 s101, 1
	s_cbranch_scc1 .Lmfskip4
	v_mfma_f32_16x16x32_bf16 v[126:129], v[156:159], v[196:199], v[126:129]
	v_mfma_f32_16x16x32_bf16 v[122:125], v[172:175], v[196:199], v[122:125]
	v_mfma_f32_16x16x32_bf16 v[110:113], v[156:159], v[204:207], v[110:113]
	v_mfma_f32_16x16x32_bf16 v[106:109], v[172:175], v[204:207], v[106:109]
	v_mfma_f32_16x16x32_bf16 v[94:97], v[156:159], v[212:215], v[94:97]
	v_mfma_f32_16x16x32_bf16 v[90:93], v[172:175], v[212:215], v[90:93]
	v_mfma_f32_16x16x32_bf16 v[78:81], v[156:159], v[220:223], v[78:81]
	v_mfma_f32_16x16x32_bf16 v[74:77], v[172:175], v[220:223], v[74:77]
	v_mfma_f32_16x16x32_bf16 v[126:129], v[160:163], v[200:203], v[126:129]
	v_mfma_f32_16x16x32_bf16 v[122:125], v[176:179], v[200:203], v[122:125]
	v_mfma_f32_16x16x32_bf16 v[110:113], v[160:163], v[208:211], v[110:113]
	v_mfma_f32_16x16x32_bf16 v[106:109], v[176:179], v[208:211], v[106:109]
	v_mfma_f32_16x16x32_bf16 v[94:97], v[160:163], v[216:219], v[94:97]
	v_mfma_f32_16x16x32_bf16 v[90:93], v[176:179], v[216:219], v[90:93]
	v_mfma_f32_16x16x32_bf16 v[78:81], v[160:163], v[224:227], v[78:81]
	v_mfma_f32_16x16x32_bf16 v[74:77], v[176:179], v[224:227], v[74:77]
	v_mfma_f32_16x16x32_bf16 v[118:121], v[180:183], v[196:199], v[118:121]
	v_mfma_f32_16x16x32_bf16 v[114:117], v[188:191], v[196:199], v[114:117]
	v_mfma_f32_16x16x32_bf16 v[102:105], v[180:183], v[204:207], v[102:105]
	v_mfma_f32_16x16x32_bf16 v[98:101], v[188:191], v[204:207], v[98:101]
	v_mfma_f32_16x16x32_bf16 v[86:89], v[180:183], v[212:215], v[86:89]
	v_mfma_f32_16x16x32_bf16 v[82:85], v[188:191], v[212:215], v[82:85]
	v_mfma_f32_16x16x32_bf16 v[70:73], v[180:183], v[220:223], v[70:73]
	v_mfma_f32_16x16x32_bf16 v[66:69], v[188:191], v[220:223], v[66:69]
	v_mfma_f32_16x16x32_bf16 v[118:121], v[184:187], v[200:203], v[118:121]
	v_mfma_f32_16x16x32_bf16 v[114:117], v[192:195], v[200:203], v[114:117]
	v_mfma_f32_16x16x32_bf16 v[102:105], v[184:187], v[208:211], v[102:105]
	v_mfma_f32_16x16x32_bf16 v[98:101], v[192:195], v[208:211], v[98:101]
	v_mfma_f32_16x16x32_bf16 v[86:89], v[184:187], v[216:219], v[86:89]
	v_mfma_f32_16x16x32_bf16 v[82:85], v[192:195], v[216:219], v[82:85]
	v_mfma_f32_16x16x32_bf16 v[70:73], v[184:187], v[224:227], v[70:73]
	v_mfma_f32_16x16x32_bf16 v[66:69], v[192:195], v[224:227], v[66:69]
; #define PG8_STAGE(bufoff, gbase, voff) do { _Pragma("unroll") for (int _i = 0; _i < 2; ++_i) \
;         __builtin_amdgcn_global_load_lds((const unsigned*)((const char*)(gbase) + (voff)[_i]), (PG8_LAS unsigned*)(lds + (bufoff) + ldsw + _i * 8192), 16, 0, 0); } while (0)
; #define PG8_LDA(dst, b, h) do { _Pragma("unroll") for (int m = 0; m < 4; ++m) _Pragma("unroll") for (int k = 0; k < 2; ++k) dst[m][k] = *(const PG8_LAS bf16x8*)(lds + PG8_SA(b, h) + aoff + m * 2048 + k * 1024); } while (0)
; #define PG8_LDB(dst, b, h) do { _Pragma("unroll") for (int n = 0; n < 2; ++n) _Pragma("unroll") for (int k = 0; k < 2; ++k) dst[n][k] = *(const PG8_LAS bf16x8*)(lds + PG8_SB(b, h) + boff + n * 2048 + k * 1024); } while (0)
; #define PG8_MMA(ai, bj, At, Bt) do { __builtin_amdgcn_s_setprio(1); _Pragma("unroll") for (int m = 0; m < 4; ++m) _Pragma("unroll") for (int n = 0; n < 2; ++n) _Pragma("unroll") for (int k = 0; k < 2; ++k) \
;         acc[ai][bj][m][n] = __builtin_amdgcn_mfma_f32_16x16x32_bf16(Bt[n][k], At[m][k], acc[ai][bj][m][n], 0, 0, 0); __builtin_amdgcn_s_setprio(0); } while (0)
; #define PG8_WAIT_V(n) asm volatile("s_waitcnt vmcnt(" #n ")" ::: "memory")
; #define PG8_WAIT_L(n) asm volatile("s_waitcnt lgkmcnt(" #n ")" ::: "memory")
; #define PG8_BAR __builtin_amdgcn_s_barrier()
; #define PG8_SCHED __builtin_amdgcn_sched_barrier(0)
;     ...
;             PG8_LDB(B0, 1, 0); PG8_LDB(B1, 1, 1); PG8_SCHED; PG8_LDA(At, 1, 0); PG8_STAGE(PG8_SA(0, 1), a2 + hstepA, voffA);
;             PG8_WAIT_V(8); PG8_WAIT_L(0); PG8_BAR; PG8_MMA(0, 0, At, B0); PG8_MMA(0, 1, At, B1); PG8_BAR; PG8_SCHED;
.Lmfskip4:
	s_barrier
	s_add_i32 s27, s27, s0
	v_lshl_add_u64 v[164:165], s[34:35], 0, v[166:167]
	s_mov_b32 m0, s27
	ds_read_b128 v[196:199], v154 offset:16384
	ds_read_b128 v[200:203], v154 offset:17408
	ds_read_b128 v[204:207], v154 offset:18432
	ds_read_b128 v[208:211], v154 offset:19456
	ds_read_b128 v[212:215], v154 offset:20480
	ds_read_b128 v[216:219], v154 offset:21504
	ds_read_b128 v[220:223], v154 offset:22528
	ds_read_b128 v[224:227], v154 offset:23552
	global_load_lds_dwordx4 v[164:165], off
	s_add_i32 m0, s27, 0x2000
	v_lshl_add_u64 v[168:169], s[34:35], 0, v[130:131]
	s_add_u32 s34, s34, s58
	s_addc_u32 s35, s35, s59
	s_add_i32 s11, s11, s0
	global_load_lds_dwordx4 v[168:169], off
	v_lshl_add_u64 v[170:171], s[34:35], 0, v[166:167]
	s_mov_b32 m0, s11
	v_lshl_add_u64 v[228:229], s[34:35], 0, v[130:131]
	global_load_lds_dwordx4 v[170:171], off
	s_add_i32 m0, s11, 0x2000
	v_lshl_add_u64 v[230:231], s[8:9], 0, v[134:135]
	global_load_lds_dwordx4 v[228:229], off
	s_mov_b32 m0, s3
	v_lshl_add_u64 v[232:233], s[8:9], 0, v[132:133]
	global_load_lds_dwordx4 v[230:231], off
	s_mov_b32 m0, s12
	s_nop 0
	global_load_lds_dwordx4 v[232:233], off
	s_waitcnt vmcnt(8)
	s_waitcnt lgkmcnt(0)
	s_barrier
	s_waitcnt lgkmcnt(0)
	s_bitcmp1_b32 s101, 0
	s_cbranch_scc1 .Lmfskip5
	v_mfma_f32_16x16x32_bf16 v[62:65], v[156:159], v[196:199], v[62:65]
	v_mfma_f32_16x16x32_bf16 v[58:61], v[172:175], v[196:199], v[58:61]
	v_mfma_f32_16x16x32_bf16 v[46:49], v[156:159], v[204:207], v[46:49]
	v_mfma_f32_16x16x32_bf16 v[42:45], v[172:175], v[204:207], v[42:45]
	v_mfma_f32_16x16x32_bf16 v[30:33], v[156:159], v[212:215], v[30:33]
	v_mfma_f32_16x16x32_bf16 v[26:29], v[172:175], v[212:215], v[26:29]
	v_mfma_f32_16x16x32_bf16 v[14:17], v[156:159], v[220:223], v[14:17]
	v_mfma_f32_16x16x32_bf16 v[10:13], v[172:175], v[220:223], v[10:13]
	v_mfma_f32_16x16x32_bf16 v[62:65], v[160:163], v[200:203], v[62:65]
	v_mfma_f32_16x16x32_bf16 v[58:61], v[176:179], v[200:203], v[58:61]
	v_mfma_f32_16x16x32_bf16 v[46:49], v[160:163], v[208:211], v[46:49]
	v_mfma_f32_16x16x32_bf16 v[42:45], v[176:179], v[208:211], v[42:45]
	v_mfma_f32_16x16x32_bf16 v[30:33], v[160:163], v[216:219], v[30:33]
	v_mfma_f32_16x16x32_bf16 v[26:29], v[176:179], v[216:219], v[26:29]
	v_mfma_f32_16x16x32_bf16 v[14:17], v[160:163], v[224:227], v[14:17]
	v_mfma_f32_16x16x32_bf16 v[10:13], v[176:179], v[224:227], v[10:13]
	v_mfma_f32_16x16x32_bf16 v[54:57], v[180:183], v[196:199], v[54:57]
	v_mfma_f32_16x16x32_bf16 v[50:53], v[188:191], v[196:199], v[50:53]
	v_mfma_f32_16x16x32_bf16 v[38:41], v[180:183], v[204:207], v[38:41]
	v_mfma_f32_16x16x32_bf16 v[34:37], v[188:191], v[204:207], v[34:37]
	v_mfma_f32_16x16x32_bf16 v[22:25], v[180:183], v[212:215], v[22:25]
	v_mfma_f32_16x16x32_bf16 v[18:21], v[188:191], v[212:215], v[18:21]
	v_mfma_f32_16x16x32_bf16 v[6:9], v[180:183], v[220:223], v[6:9]
	v_mfma_f32_16x16x32_bf16 v[2:5], v[188:191], v[220:223], v[2:5]
	v_mfma_f32_16x16x32_bf16 v[54:57], v[184:187], v[200:203], v[54:57]
	v_mfma_f32_16x16x32_bf16 v[50:53], v[192:195], v[200:203], v[50:53]
	v_mfma_f32_16x16x32_bf16 v[38:41], v[184:187], v[208:211], v[38:41]
	v_mfma_f32_16x16x32_bf16 v[34:37], v[192:195], v[208:211], v[34:37]
	v_mfma_f32_16x16x32_bf16 v[22:25], v[184:187], v[216:219], v[22:25]
	v_mfma_f32_16x16x32_bf16 v[18:21], v[192:195], v[216:219], v[18:21]
	v_mfma_f32_16x16x32_bf16 v[6:9], v[184:187], v[224:227], v[6:9]
	v_mfma_f32_16x16x32_bf16 v[2:5], v[192:195], v[224:227], v[2:5]

;     ...
;         for (int t = 0; t < nt; t += 2) {
;             const bool last = (t == nt - 2);
;             const char* a1 = cA + (size_t)(t + 1) * kstep;
;             const char* a2 = last ? nA : cA + (size_t)(t + 2) * kstep; const char* b2 = last ? nB : cB + (size_t)(t + 2) * kstep;
;             const char* a3 = a2 + kstep; const char* b3 = b2 + kstep;
.Lmfskip7:
	s_barrier
	s_add_u32 s24, s24, 0x100
	s_addc_u32 s25, s25, 0
	s_add_u32 s6, s6, 0x100
	s_addc_u32 s7, s7, 0
	s_cmp_ge_i32 s10, s15
	s_mov_b32 s8, s10
	s_cbranch_scc0 .Lhalf_613
	s_branch .LBB0_614
